# tail-fill weight conversion + non-temporal (nt) loads and stores in the conversion loop so the streamed weights do not evict the GEMM operand panels from L2
# speedup vs baseline: 1.0183x; 1.0084x over previous
.LBB0_38:
	v_add_u32_e32 v34, v115, v118
	s_waitcnt vmcnt(0)
	ds_write2_b32 v34, v2, v3 offset1:1
	ds_write2_b32 v34, v4, v5 offset0:2 offset1:3
	v_add_u32_e32 v2, 0x420, v34
	ds_write2_b32 v2, v6, v7 offset1:1
	v_add_u32_e32 v2, 0x428, v34
	ds_write2_b32 v2, v8, v9 offset1:1
	v_add_u32_e32 v2, 0x840, v34
	ds_write2_b32 v2, v14, v15 offset1:1
	v_add_u32_e32 v2, 0x848, v34
	ds_write2_b32 v2, v16, v17 offset1:1
	v_add_u32_e32 v2, 0xc60, v34
	ds_write2_b32 v2, v10, v11 offset1:1
	v_add_u32_e32 v2, 0xc68, v34
	ds_write2_b32 v2, v12, v13 offset1:1
	v_add_u32_e32 v2, 0x1080, v34
	ds_write2_b32 v2, v22, v23 offset1:1
	v_add_u32_e32 v2, 0x1088, v34
	ds_write2_b32 v2, v24, v25 offset1:1
	v_add_u32_e32 v2, 0x14a0, v34
	ds_write2_b32 v2, v18, v19 offset1:1
	v_add_u32_e32 v2, 0x14a8, v34
	ds_write2_b32 v2, v20, v21 offset1:1
	v_add_u32_e32 v2, 0x18c0, v34
	ds_write2_b32 v2, v30, v31 offset1:1
	v_add_u32_e32 v2, 0x18c8, v34
	ds_write2_b32 v2, v32, v33 offset1:1
	v_add_u32_e32 v2, 0x1ce0, v34
	ds_write2_b32 v2, v26, v27 offset1:1
	v_add_u32_e32 v2, 0x1ce8, v34
	ds_write2_b32 v2, v28, v29 offset1:1
	s_waitcnt lgkmcnt(0)
	s_add_u32 s6, s17, s35
	s_addc_u32 s10, s18, s9
	s_ashr_i32 s9, s8, 31
	ds_read2_b32 v[6:7], v122 offset0:33 offset1:41
	ds_read2_b32 v[8:9], v122 offset1:8
	ds_read2_b32 v[10:11], v122 offset0:66 offset1:74
	ds_read2_b32 v[12:13], v122 offset0:99 offset1:107
	ds_read2_b32 v[14:15], v122 offset0:132 offset1:140
	ds_read2_b32 v[16:17], v122 offset0:165 offset1:173
	ds_read2_b32 v[18:19], v122 offset0:198 offset1:206
	ds_read2_b32 v[20:21], v122 offset0:231 offset1:239
	s_lshl_b64 s[2:3], s[8:9], 1
	s_add_u32 s2, s6, s2
	v_add_u32_e32 v24, s34, v1
	s_addc_u32 s3, s10, s3
	v_lshlrev_b32_e32 v34, 1, v114
	v_ashrrev_i32_e32 v25, 31, v24
	v_lshl_add_u64 v[22:23], s[2:3], 0, v[34:35]
	v_lshlrev_b64 v[24:25], 12, v[24:25]
	s_waitcnt lgkmcnt(6)
	v_cvt_pk_bf16_f32 v2, v8, v6
	s_waitcnt lgkmcnt(4)
	v_cvt_pk_bf16_f32 v3, v10, v12
	s_waitcnt lgkmcnt(2)
	v_cvt_pk_bf16_f32 v4, v14, v16
	s_waitcnt lgkmcnt(0)
	v_cvt_pk_bf16_f32 v5, v18, v20
	v_lshl_add_u64 v[24:25], v[22:23], 0, v[24:25]
	v_add_u32_e32 v6, s34, v119
	global_store_dwordx4 v[24:25], v[2:5], off nt
	s_nop 1
	v_cvt_pk_bf16_f32 v2, v9, v7
	v_ashrrev_i32_e32 v7, 31, v6
	v_cvt_pk_bf16_f32 v3, v11, v13
	v_cvt_pk_bf16_f32 v4, v15, v17
	v_cvt_pk_bf16_f32 v5, v19, v21
	v_lshlrev_b64 v[6:7], 12, v[6:7]
	ds_read2_b32 v[8:9], v122 offset0:49 offset1:57
	ds_read2_b32 v[10:11], v122 offset0:16 offset1:24
	ds_read2_b32 v[12:13], v122 offset0:82 offset1:90
	ds_read2_b32 v[14:15], v122 offset0:115 offset1:123
	ds_read2_b32 v[16:17], v122 offset0:148 offset1:156
	ds_read2_b32 v[18:19], v122 offset0:181 offset1:189
	ds_read2_b32 v[20:21], v122 offset0:214 offset1:222
	ds_read2_b32 v[24:25], v122 offset0:247 offset1:255
	v_lshl_add_u64 v[6:7], v[22:23], 0, v[6:7]
	global_store_dwordx4 v[6:7], v[2:5], off nt
	v_add_u32_e32 v6, s34, v120
	v_ashrrev_i32_e32 v7, 31, v6
	v_lshlrev_b64 v[6:7], 12, v[6:7]
	s_waitcnt lgkmcnt(6)
	v_cvt_pk_bf16_f32 v2, v10, v8
	s_waitcnt lgkmcnt(4)
	v_cvt_pk_bf16_f32 v3, v12, v14
	s_waitcnt lgkmcnt(2)
	v_cvt_pk_bf16_f32 v4, v16, v18
	s_waitcnt lgkmcnt(0)
	v_cvt_pk_bf16_f32 v5, v20, v24
	v_lshl_add_u64 v[6:7], v[22:23], 0, v[6:7]
	global_store_dwordx4 v[6:7], v[2:5], off nt
	v_add_u32_e32 v6, s34, v121
	v_ashrrev_i32_e32 v7, 31, v6
	v_lshlrev_b64 v[6:7], 12, v[6:7]
	v_cvt_pk_bf16_f32 v2, v11, v9
	v_cvt_pk_bf16_f32 v3, v13, v15
	v_cvt_pk_bf16_f32 v4, v17, v19
	v_cvt_pk_bf16_f32 v5, v21, v25
	v_lshl_add_u64 v[6:7], v[22:23], 0, v[6:7]
	global_store_dwordx4 v[6:7], v[2:5], off nt
	s_waitcnt lgkmcnt(0)

.LBB0_40:
	s_mov_b32 s90, 0
	s_cmp_ge_u32 s98, 0x2b00
	s_cselect_b32 s90, 0x8100, s90
	s_cmp_ge_u32 s98, 0x4080
	s_cselect_b32 s90, 0xc180, s90
	s_cmp_ge_u32 s98, 0x6180
	s_cselect_b32 s90, 0xffffc980, s90
	s_cmp_ge_u32 s98, 0x8c80
	s_cselect_b32 s90, 0x3500, s90
	s_cmp_ge_u32 s98, 0xa200
	s_cselect_b32 s90, 0xffffb400, s90
	s_cmp_ge_u32 s98, 0xcd00
	s_cselect_b32 s90, 0xa00, s90
	s_cmp_ge_u32 s98, 0xe280
	s_cselect_b32 s90, 0x4080, s90
	s_cmp_ge_u32 s98, 0xee80
	s_cselect_b32 s90, 0x4880, s90
	s_cmp_ge_u32 s98, 0xf200
	s_cselect_b32 s90, 0x3d00, s90
	s_cmp_ge_u32 s98, 0xfa00
	s_cselect_b32 s90, 0xffff8700, s90
	s_cmp_ge_u32 s98, 0x12500
	s_cselect_b32 s90, 0xffffc780, s90
	s_add_i32 s90, s90, s98
	s_add_i32 s19, s90, 0xfffec680
	s_lshl_b32 s20, s90, 4
	s_lshl_b32 s22, s90, 5
	s_add_i32 s80, s90, 0xffff5400
	s_cmp_gt_i32 s90, 0xabff
	s_mov_b64 s[2:3], -1
	s_cbranch_scc0 .LBB0_134
	s_cmp_gt_u32 s90, 0x101ff
	s_cbranch_scc0 .LBB0_115
	s_cmp_gt_u32 s90, 0x11aff
	s_cbranch_scc0 .LBB0_80
	s_cmp_gt_u32 s90, 0x122ff
	s_cbranch_scc0 .LBB0_77
	s_cmp_gt_u32 s90, 0x12eff
	s_cbranch_scc0 .LBB0_58
	s_cmp_gt_u32 s90, 0x136ff
	s_cbranch_scc0 .LBB0_55
	s_cmp_gt_u32 s90, 0x1387f
	s_cbranch_scc0 .LBB0_52
	s_cmp_gt_u32 s90, 0x1397f
	s_cbranch_scc0 .LBB0_49
	s_lshr_b32 s2, s19, 3
	s_bfe_u32 s3, s19, 0x30003
	v_readlane_b32 s52, v252, 18
	s_bitcmp0_b32 s90, 6
	v_readlane_b32 s60, v252, 26
	v_readlane_b32 s61, v252, 27
	v_readlane_b32 s64, v252, 30
	v_readlane_b32 s65, v252, 31
	s_cselect_b32 s10, s61, s65
	s_cselect_b32 s11, s60, s64
	s_lshr_b32 s6, s19, 4
	s_and_b32 s6, s6, 0xffffff8
	s_or_b32 s6, s6, s3
	s_lshl_b64 s[8:9], s[6:7], 16
	s_add_u32 s8, s11, s8
	s_mov_b32 s3, s7
	s_addc_u32 s9, s10, s9
	s_lshl_b64 s[2:3], s[2:3], 15
	s_add_u32 s2, s13, s2
	s_addc_u32 s3, s14, s3
	s_and_b32 s10, s20, 64
	v_add_u32_e32 v2, s10, v1
	v_ashrrev_i32_e32 v3, 31, v2
	s_and_b32 s11, s22, 0x60
	v_lshlrev_b64 v[2:3], 9, v[2:3]
	v_lshl_add_u64 v[2:3], s[8:9], 0, v[2:3]
	s_lshl_b32 s6, s11, 2
	v_lshl_add_u64 v[2:3], v[2:3], 0, s[6:7]
	v_lshlrev_b32_e32 v34, 2, v112
	v_lshl_add_u64 v[30:31], v[2:3], 0, v[34:35]
	s_movk_i32 s6, 0x2000
	v_add_co_u32_e32 v10, vcc, s6, v30
	s_movk_i32 s6, 0x4000
	s_nop 0
	v_addc_co_u32_e32 v11, vcc, 0, v31, vcc
	v_add_co_u32_e32 v18, vcc, s6, v30
	s_movk_i32 s6, 0x6000
	s_nop 0
	v_addc_co_u32_e32 v19, vcc, 0, v31, vcc
	v_add_co_u32_e32 v26, vcc, s6, v30
	global_load_dwordx4 v[2:5], v[30:31], off nt
	s_nop 0
	v_addc_co_u32_e32 v27, vcc, 0, v31, vcc
	global_load_dwordx4 v[6:9], v[10:11], off offset:-4096 nt
	s_nop 0
	global_load_dwordx4 v[10:13], v[10:11], off nt
	s_nop 0
	global_load_dwordx4 v[14:17], v[18:19], off offset:-4096 nt
	s_nop 0
	global_load_dwordx4 v[18:21], v[18:19], off nt
	s_nop 0
	global_load_dwordx4 v[22:25], v[26:27], off offset:-4096 nt
	s_nop 0
	global_load_dwordx4 v[26:29], v[26:27], off nt
	s_movk_i32 s6, 0x7000
	v_add_co_u32_e32 v30, vcc, s6, v30
	v_add_u32_e32 v134, v115, v118
	s_nop 0
	v_addc_co_u32_e32 v31, vcc, 0, v31, vcc
	global_load_dwordx4 v[30:33], v[30:31], off nt
	v_add_u32_e32 v135, 0x420, v134
	v_add_u32_e32 v136, 0x428, v134
	v_add_u32_e32 v137, 0x840, v134
	v_add_u32_e32 v138, 0x848, v134
	v_add_u32_e32 v139, 0xc60, v134
	v_add_u32_e32 v140, 0xc68, v134
	v_add_u32_e32 v141, 0x1080, v134
	v_add_u32_e32 v142, 0x1088, v134
	v_add_u32_e32 v143, 0x14a0, v134
	v_add_u32_e32 v144, 0x14a8, v134
	v_add_u32_e32 v145, 0x18c0, v134
	v_add_u32_e32 v146, 0x18c8, v134
	v_add_u32_e32 v147, 0x1ce0, v134
	v_add_u32_e32 v148, 0x1ce8, v134
	s_lshl_b32 s6, s10, 1
	v_add_u32_e32 v116, s11, v1
	s_add_u32 s2, s2, s6
	v_ashrrev_i32_e32 v117, 31, v116
	s_addc_u32 s3, s3, 0
	v_lshlrev_b32_e32 v34, 1, v114
	v_lshlrev_b64 v[116:117], 8, v[116:117]
	v_lshl_add_u64 v[132:133], s[2:3], 0, v[34:35]
	v_readlane_b32 s53, v252, 19
	v_readlane_b32 s54, v252, 20
	v_readlane_b32 s55, v252, 21
	v_readlane_b32 s56, v252, 22
	v_readlane_b32 s57, v252, 23
	v_readlane_b32 s58, v252, 24
	v_readlane_b32 s59, v252, 25
	v_readlane_b32 s62, v252, 28
	v_readlane_b32 s63, v252, 29
	v_readlane_b32 s66, v252, 32
	v_readlane_b32 s67, v252, 33
	s_mov_b64 s[2:3], 0
	s_waitcnt vmcnt(7)
	ds_write2_b32 v134, v2, v3 offset1:1
	ds_write2_b32 v134, v4, v5 offset0:2 offset1:3
	s_waitcnt vmcnt(6)
	ds_write2_b32 v135, v6, v7 offset1:1
	ds_write2_b32 v136, v8, v9 offset1:1
	s_waitcnt vmcnt(5)
	ds_write2_b32 v137, v10, v11 offset1:1
	ds_write2_b32 v138, v12, v13 offset1:1
	s_waitcnt vmcnt(4)
	ds_write2_b32 v139, v14, v15 offset1:1
	ds_write2_b32 v140, v16, v17 offset1:1
	s_waitcnt vmcnt(3)
	ds_write2_b32 v141, v18, v19 offset1:1
	ds_write2_b32 v142, v20, v21 offset1:1
	s_waitcnt vmcnt(2)
	ds_write2_b32 v143, v22, v23 offset1:1
	ds_write2_b32 v144, v24, v25 offset1:1
	s_waitcnt vmcnt(1)
	ds_write2_b32 v145, v26, v27 offset1:1
	ds_write2_b32 v146, v28, v29 offset1:1
	s_waitcnt vmcnt(0)
	ds_write2_b32 v147, v30, v31 offset1:1
	ds_write2_b32 v148, v32, v33 offset1:1
	s_waitcnt lgkmcnt(0)
	ds_read2_b32 v[6:7], v122 offset0:33 offset1:41
	ds_read2_b32 v[8:9], v122 offset1:8
	ds_read2_b32 v[10:11], v122 offset0:66 offset1:74
	ds_read2_b32 v[12:13], v122 offset0:99 offset1:107
	ds_read2_b32 v[14:15], v122 offset0:132 offset1:140
	ds_read2_b32 v[16:17], v122 offset0:165 offset1:173
	ds_read2_b32 v[18:19], v122 offset0:198 offset1:206
	ds_read2_b32 v[20:21], v122 offset0:231 offset1:239
	v_lshl_add_u64 v[22:23], v[132:133], 0, v[116:117]
	s_waitcnt lgkmcnt(6)
	v_cvt_pk_bf16_f32 v2, v8, v6
	s_waitcnt lgkmcnt(4)
	v_cvt_pk_bf16_f32 v3, v10, v12
	s_waitcnt lgkmcnt(2)
	v_cvt_pk_bf16_f32 v4, v14, v16
	s_waitcnt lgkmcnt(0)
	v_cvt_pk_bf16_f32 v5, v18, v20
	global_store_dwordx4 v[22:23], v[2:5], off nt
	v_cvt_pk_bf16_f32 v6, v9, v7
	v_cvt_pk_bf16_f32 v7, v11, v13
	v_add_u32_e32 v2, s11, v119
	v_ashrrev_i32_e32 v3, 31, v2
	v_cvt_pk_bf16_f32 v8, v15, v17
	v_cvt_pk_bf16_f32 v9, v19, v21
	v_lshlrev_b64 v[2:3], 8, v[2:3]
	ds_read2_b32 v[10:11], v122 offset0:49 offset1:57
	ds_read2_b32 v[12:13], v122 offset0:16 offset1:24
	ds_read2_b32 v[14:15], v122 offset0:82 offset1:90
	ds_read2_b32 v[16:17], v122 offset0:115 offset1:123
	ds_read2_b32 v[18:19], v122 offset0:148 offset1:156
	ds_read2_b32 v[20:21], v122 offset0:181 offset1:189
	ds_read2_b32 v[22:23], v122 offset0:214 offset1:222
	ds_read2_b32 v[24:25], v122 offset0:247 offset1:255
	v_lshl_add_u64 v[2:3], v[132:133], 0, v[2:3]
	global_store_dwordx4 v[2:3], v[6:9], off nt
	s_waitcnt lgkmcnt(6)
	v_cvt_pk_bf16_f32 v2, v12, v10
	s_waitcnt lgkmcnt(4)
	v_cvt_pk_bf16_f32 v3, v14, v16
	v_add_u32_e32 v6, s11, v120
	v_ashrrev_i32_e32 v7, 31, v6
	v_lshlrev_b64 v[6:7], 8, v[6:7]
	s_waitcnt lgkmcnt(2)
	v_cvt_pk_bf16_f32 v4, v18, v20
	s_waitcnt lgkmcnt(0)
	v_cvt_pk_bf16_f32 v5, v22, v24
	v_lshl_add_u64 v[6:7], v[132:133], 0, v[6:7]
	global_store_dwordx4 v[6:7], v[2:5], off nt
	v_add_u32_e32 v6, s11, v121
	v_ashrrev_i32_e32 v7, 31, v6
	v_lshlrev_b64 v[6:7], 8, v[6:7]
	v_cvt_pk_bf16_f32 v2, v13, v11
	v_cvt_pk_bf16_f32 v3, v15, v17
	v_cvt_pk_bf16_f32 v4, v19, v21
	v_cvt_pk_bf16_f32 v5, v23, v25
	v_lshl_add_u64 v[6:7], v[132:133], 0, v[6:7]
	global_store_dwordx4 v[6:7], v[2:5], off nt
	s_waitcnt lgkmcnt(0)
.LBB0_49:
	s_andn2_b64 vcc, exec, s[2:3]
	s_cbranch_vccnz .LBB0_51
	s_and_b32 s2, s90, 0x1ffc0
	s_and_b32 s3, s90, 63
	s_add_i32 s2, s2, 0xfffec780
	s_lshl_b32 s8, s3, 5
	s_cmp_lt_u32 s3, 32
	s_mov_b64 s[26:27], s[72:73]
	s_mov_b32 s3, s74
	s_mov_b32 s6, s75
	s_mov_b64 s[10:11], s[78:79]
	v_readlane_b32 s64, v252, 34
	v_add_u32_e32 v2, s2, v1
	v_readlane_b32 s72, v252, 42
	v_readlane_b32 s73, v252, 43
	v_readlane_b32 s74, v252, 44
	v_readlane_b32 s75, v252, 45
	v_readlane_b32 s78, v252, 48
	v_readlane_b32 s79, v252, 49
	v_ashrrev_i32_e32 v3, 31, v2
	s_mov_b64 s[78:79], s[10:11]
	s_cselect_b32 s11, s73, s75
	s_cselect_b32 s10, s72, s74
	s_mov_b32 s74, s3
	v_lshlrev_b64 v[2:3], 12, v[2:3]
	s_lshl_b32 s3, s90, 7
	s_mov_b32 s75, s6
	v_lshl_add_u64 v[2:3], s[10:11], 0, v[2:3]
	s_and_b32 s6, s3, 0xf80
	v_lshl_add_u64 v[2:3], v[2:3], 0, s[6:7]
	v_lshlrev_b32_e32 v34, 2, v112
	v_lshl_add_u64 v[30:31], v[2:3], 0, v[34:35]
	s_mov_b32 s3, 0x8000
	v_add_co_u32_e32 v6, vcc, s3, v30
	s_mov_b32 s3, 0x28000
	s_nop 0
	v_addc_co_u32_e32 v7, vcc, 0, v31, vcc
	v_add_co_u32_e32 v10, vcc, s81, v30
	global_load_dwordx4 v[2:5], v[30:31], off nt
	s_nop 0
	global_load_dwordx4 v[6:9], v[6:7], off nt
	v_addc_co_u32_e32 v11, vcc, 0, v31, vcc
	v_add_co_u32_e32 v14, vcc, s82, v30
	v_add_u32_e32 v34, v115, v118
	s_nop 0
	v_addc_co_u32_e32 v15, vcc, 0, v31, vcc
	v_add_co_u32_e32 v18, vcc, s83, v30
	global_load_dwordx4 v[10:13], v[10:11], off nt
	s_nop 0
	global_load_dwordx4 v[14:17], v[14:15], off nt
	v_addc_co_u32_e32 v19, vcc, 0, v31, vcc
	v_add_co_u32_e32 v22, vcc, s3, v30
	s_mov_b32 s3, 0x38000
	s_nop 0
	v_addc_co_u32_e32 v23, vcc, 0, v31, vcc
	global_load_dwordx4 v[18:21], v[18:19], off nt
	s_nop 0
	global_load_dwordx4 v[22:25], v[22:23], off nt
	v_add_co_u32_e32 v26, vcc, s84, v30
	v_add_u32_e32 v116, 0x420, v34
	s_nop 0
	v_addc_co_u32_e32 v27, vcc, 0, v31, vcc
	global_load_dwordx4 v[26:29], v[26:27], off nt
	v_add_co_u32_e32 v30, vcc, s3, v30
	v_add_u32_e32 v117, 0x428, v34
	s_nop 0
	v_addc_co_u32_e32 v31, vcc, 0, v31, vcc
	global_load_dwordx4 v[30:33], v[30:31], off nt
	v_add_u32_e32 v132, 0x840, v34
	v_add_u32_e32 v133, 0x848, v34
	v_add_u32_e32 v134, 0xc60, v34
	v_add_u32_e32 v135, 0xc68, v34
	v_add_u32_e32 v136, 0x1080, v34
	v_add_u32_e32 v137, 0x1088, v34
	v_add_u32_e32 v138, 0x14a0, v34
	v_add_u32_e32 v139, 0x14a8, v34
	v_add_u32_e32 v140, 0x18c0, v34
	v_add_u32_e32 v141, 0x18c8, v34
	v_add_u32_e32 v142, 0x1ce0, v34
	v_add_u32_e32 v143, 0x1ce8, v34
	s_mov_b32 s3, s7
	s_mov_b64 s[72:73], s[26:27]
	v_readlane_b32 s65, v252, 35
	v_readlane_b32 s66, v252, 36
	v_readlane_b32 s67, v252, 37
	v_readlane_b32 s68, v252, 38
	v_readlane_b32 s69, v252, 39
	v_readlane_b32 s70, v252, 40
	v_readlane_b32 s71, v252, 41
	v_readlane_b32 s76, v252, 46
	v_readlane_b32 s77, v252, 47
	s_waitcnt vmcnt(7)
	ds_write2_b32 v34, v2, v3 offset1:1
	ds_write2_b32 v34, v4, v5 offset0:2 offset1:3
	s_waitcnt vmcnt(6)
	ds_write2_b32 v116, v6, v7 offset1:1
	ds_write2_b32 v117, v8, v9 offset1:1
	s_waitcnt vmcnt(5)
	ds_write2_b32 v132, v10, v11 offset1:1
	ds_write2_b32 v133, v12, v13 offset1:1
	s_waitcnt vmcnt(4)
	ds_write2_b32 v134, v14, v15 offset1:1
	ds_write2_b32 v135, v16, v17 offset1:1
	s_waitcnt vmcnt(3)
	ds_write2_b32 v136, v18, v19 offset1:1
	ds_write2_b32 v137, v20, v21 offset1:1
	s_waitcnt vmcnt(2)
	ds_write2_b32 v138, v22, v23 offset1:1
	ds_write2_b32 v139, v24, v25 offset1:1
	s_waitcnt vmcnt(1)
	ds_write2_b32 v140, v26, v27 offset1:1
	ds_write2_b32 v141, v28, v29 offset1:1
	s_waitcnt vmcnt(0)
	ds_write2_b32 v142, v30, v31 offset1:1
	ds_write2_b32 v143, v32, v33 offset1:1
	s_waitcnt lgkmcnt(0)
	ds_read2_b32 v[6:7], v122 offset0:33 offset1:41
	ds_read2_b32 v[8:9], v122 offset1:8
	ds_read2_b32 v[10:11], v122 offset0:66 offset1:74
	ds_read2_b32 v[12:13], v122 offset0:99 offset1:107
	ds_read2_b32 v[14:15], v122 offset0:132 offset1:140
	ds_read2_b32 v[16:17], v122 offset0:165 offset1:173
	ds_read2_b32 v[18:19], v122 offset0:198 offset1:206
	ds_read2_b32 v[20:21], v122 offset0:231 offset1:239
	v_add_u32_e32 v24, s8, v1
	v_ashrrev_i32_e32 v25, 31, v24
	v_lshl_add_u64 v[22:23], s[2:3], 1, v[62:63]
	v_lshlrev_b64 v[24:25], 9, v[24:25]
	s_waitcnt lgkmcnt(6)
	v_cvt_pk_bf16_f32 v2, v8, v6
	s_waitcnt lgkmcnt(4)
	v_cvt_pk_bf16_f32 v3, v10, v12
	s_waitcnt lgkmcnt(2)
	v_cvt_pk_bf16_f32 v4, v14, v16
	s_waitcnt lgkmcnt(0)
	v_cvt_pk_bf16_f32 v5, v18, v20
	v_lshl_add_u64 v[24:25], v[22:23], 0, v[24:25]
	v_add_u32_e32 v6, s8, v119
	global_store_dwordx4 v[24:25], v[2:5], off nt
	s_nop 1
	v_cvt_pk_bf16_f32 v2, v9, v7
	v_ashrrev_i32_e32 v7, 31, v6
	v_cvt_pk_bf16_f32 v3, v11, v13
	v_cvt_pk_bf16_f32 v4, v15, v17
	v_cvt_pk_bf16_f32 v5, v19, v21
	v_lshlrev_b64 v[6:7], 9, v[6:7]
	ds_read2_b32 v[8:9], v122 offset0:49 offset1:57
	ds_read2_b32 v[10:11], v122 offset0:16 offset1:24
	ds_read2_b32 v[12:13], v122 offset0:82 offset1:90
	ds_read2_b32 v[14:15], v122 offset0:115 offset1:123
	ds_read2_b32 v[16:17], v122 offset0:148 offset1:156
	ds_read2_b32 v[18:19], v122 offset0:181 offset1:189
	ds_read2_b32 v[20:21], v122 offset0:214 offset1:222
	ds_read2_b32 v[24:25], v122 offset0:247 offset1:255
	v_lshl_add_u64 v[6:7], v[22:23], 0, v[6:7]
	global_store_dwordx4 v[6:7], v[2:5], off nt
	v_add_u32_e32 v6, s8, v120
	v_ashrrev_i32_e32 v7, 31, v6
	v_lshlrev_b64 v[6:7], 9, v[6:7]
	s_waitcnt lgkmcnt(6)
	v_cvt_pk_bf16_f32 v2, v10, v8
	s_waitcnt lgkmcnt(4)
	v_cvt_pk_bf16_f32 v3, v12, v14
	s_waitcnt lgkmcnt(2)
	v_cvt_pk_bf16_f32 v4, v16, v18
	s_waitcnt lgkmcnt(0)
	v_cvt_pk_bf16_f32 v5, v20, v24
	v_lshl_add_u64 v[6:7], v[22:23], 0, v[6:7]
	global_store_dwordx4 v[6:7], v[2:5], off nt
	v_add_u32_e32 v6, s8, v121
	v_ashrrev_i32_e32 v7, 31, v6
	v_lshlrev_b64 v[6:7], 9, v[6:7]
	v_cvt_pk_bf16_f32 v2, v11, v9
	v_cvt_pk_bf16_f32 v3, v13, v15
	v_cvt_pk_bf16_f32 v4, v17, v19
	v_cvt_pk_bf16_f32 v5, v21, v25
	v_lshl_add_u64 v[6:7], v[22:23], 0, v[6:7]
	global_store_dwordx4 v[6:7], v[2:5], off nt
	s_waitcnt lgkmcnt(0)

.LBB0_52:
	s_andn2_b64 vcc, exec, s[2:3]
	s_cbranch_vccnz .LBB0_54
	s_add_i32 s2, s90, 0xc900
	s_and_b32 s3, s2, 0xffff
	s_mul_i32 s3, s3, 0xaaab
	s_lshr_b32 s3, s3, 21
	s_mul_i32 s6, s3, 48
	s_sub_i32 s2, s2, s6
	s_mov_b64 s[8:9], s[72:73]
	s_mov_b32 s6, s74
	s_mov_b32 s10, s75
	s_mov_b64 s[26:27], s[78:79]
	v_readlane_b32 s64, v252, 34
	s_lshl_b32 s2, s2, 5
	v_readlane_b32 s70, v252, 40
	v_readlane_b32 s71, v252, 41
	v_readlane_b32 s74, v252, 44
	s_and_b32 s2, s2, 0xffe0
	v_lshl_add_u32 v4, s3, 6, v1
	v_readlane_b32 s72, v252, 42
	v_readlane_b32 s73, v252, 43
	s_mov_b32 s74, s6
	v_mov_b64_e32 v[2:3], s[70:71]
	s_movk_i32 s6, 0x1800
	s_mov_b64 s[72:73], s[8:9]
	v_mad_i64_i32 v[2:3], s[8:9], v4, s6, v[2:3]
	s_lshl_b32 s6, s2, 2
	v_lshl_add_u64 v[2:3], v[2:3], 0, s[6:7]
	v_lshlrev_b32_e32 v34, 2, v112
	v_lshl_add_u64 v[30:31], v[2:3], 0, v[34:35]
	s_mov_b32 s6, 0xc000
	v_add_co_u32_e32 v6, vcc, s6, v30
	s_mov_b32 s6, 0x24000
	s_nop 0
	v_addc_co_u32_e32 v7, vcc, 0, v31, vcc
	v_add_co_u32_e32 v10, vcc, s82, v30
	global_load_dwordx4 v[2:5], v[30:31], off nt
	s_nop 0
	global_load_dwordx4 v[6:9], v[6:7], off nt
	v_addc_co_u32_e32 v11, vcc, 0, v31, vcc
	v_add_co_u32_e32 v14, vcc, s6, v30
	s_mov_b32 s6, 0x3c000
	s_nop 0
	v_addc_co_u32_e32 v15, vcc, 0, v31, vcc
	v_add_co_u32_e32 v18, vcc, s84, v30
	global_load_dwordx4 v[10:13], v[10:11], off nt
	s_nop 0
	global_load_dwordx4 v[14:17], v[14:15], off nt
	v_addc_co_u32_e32 v19, vcc, 0, v31, vcc
	v_add_co_u32_e32 v22, vcc, s6, v30
	s_mov_b32 s6, 0x48000
	s_nop 0
	v_addc_co_u32_e32 v23, vcc, 0, v31, vcc
	global_load_dwordx4 v[18:21], v[18:19], off nt
	s_nop 0
	global_load_dwordx4 v[22:25], v[22:23], off nt
	v_add_co_u32_e32 v26, vcc, s6, v30
	s_mov_b32 s6, 0x54000
	s_nop 0
	v_addc_co_u32_e32 v27, vcc, 0, v31, vcc
	global_load_dwordx4 v[26:29], v[26:27], off nt
	v_add_co_u32_e32 v30, vcc, s6, v30
	v_add_u32_e32 v34, v115, v118
	s_nop 0
	v_addc_co_u32_e32 v31, vcc, 0, v31, vcc
	global_load_dwordx4 v[30:33], v[30:31], off nt
	v_add_u32_e32 v134, 0x420, v34
	v_add_u32_e32 v135, 0x428, v34
	v_add_u32_e32 v136, 0x840, v34
	v_add_u32_e32 v137, 0x848, v34
	v_add_u32_e32 v138, 0xc60, v34
	v_add_u32_e32 v139, 0xc68, v34
	v_add_u32_e32 v140, 0x1080, v34
	v_add_u32_e32 v141, 0x1088, v34
	v_add_u32_e32 v142, 0x14a0, v34
	v_add_u32_e32 v143, 0x14a8, v34
	v_add_u32_e32 v144, 0x18c0, v34
	v_add_u32_e32 v145, 0x18c8, v34
	v_add_u32_e32 v146, 0x1ce0, v34
	v_add_u32_e32 v147, 0x1ce8, v34
	v_add_u32_e32 v116, s2, v1
	s_lshl_b32 s6, s3, 7
	v_ashrrev_i32_e32 v117, 31, v116
	v_lshl_add_u64 v[132:133], v[64:65], 0, s[6:7]
	v_readlane_b32 s75, v252, 45
	v_readlane_b32 s78, v252, 48
	v_readlane_b32 s79, v252, 49
	s_mov_b64 s[78:79], s[26:27]
	s_mov_b32 s75, s10
	v_readlane_b32 s65, v252, 35
	v_readlane_b32 s66, v252, 36
	v_readlane_b32 s67, v252, 37
	v_readlane_b32 s68, v252, 38
	v_readlane_b32 s69, v252, 39
	v_readlane_b32 s76, v252, 46
	v_readlane_b32 s77, v252, 47
	s_waitcnt vmcnt(7)
	ds_write2_b32 v34, v2, v3 offset1:1
	ds_write2_b32 v34, v4, v5 offset0:2 offset1:3
	s_waitcnt vmcnt(6)
	ds_write2_b32 v134, v6, v7 offset1:1
	ds_write2_b32 v135, v8, v9 offset1:1
	s_waitcnt vmcnt(5)
	ds_write2_b32 v136, v10, v11 offset1:1
	ds_write2_b32 v137, v12, v13 offset1:1
	s_waitcnt vmcnt(4)
	ds_write2_b32 v138, v14, v15 offset1:1
	ds_write2_b32 v139, v16, v17 offset1:1
	s_waitcnt vmcnt(3)
	ds_write2_b32 v140, v18, v19 offset1:1
	ds_write2_b32 v141, v20, v21 offset1:1
	s_waitcnt vmcnt(2)
	ds_write2_b32 v142, v22, v23 offset1:1
	ds_write2_b32 v143, v24, v25 offset1:1
	s_waitcnt vmcnt(1)
	ds_write2_b32 v144, v26, v27 offset1:1
	ds_write2_b32 v145, v28, v29 offset1:1
	s_waitcnt vmcnt(0)
	ds_write2_b32 v146, v30, v31 offset1:1
	ds_write2_b32 v147, v32, v33 offset1:1
	s_waitcnt lgkmcnt(0)
	ds_read2_b32 v[6:7], v122 offset0:33 offset1:41
	ds_read2_b32 v[8:9], v122 offset1:8
	ds_read2_b32 v[10:11], v122 offset0:66 offset1:74
	ds_read2_b32 v[12:13], v122 offset0:99 offset1:107
	ds_read2_b32 v[14:15], v122 offset0:132 offset1:140
	ds_read2_b32 v[16:17], v122 offset0:165 offset1:173
	ds_read2_b32 v[18:19], v122 offset0:198 offset1:206
	ds_read2_b32 v[20:21], v122 offset0:231 offset1:239
	v_lshlrev_b64 v[22:23], 10, v[116:117]
	s_waitcnt lgkmcnt(6)
	v_cvt_pk_bf16_f32 v2, v8, v6
	s_waitcnt lgkmcnt(4)
	v_cvt_pk_bf16_f32 v3, v10, v12
	s_waitcnt lgkmcnt(2)
	v_cvt_pk_bf16_f32 v4, v14, v16
	s_waitcnt lgkmcnt(0)
	v_cvt_pk_bf16_f32 v5, v18, v20
	v_lshl_add_u64 v[22:23], v[132:133], 0, v[22:23]
	v_add_u32_e32 v6, s2, v119
	global_store_dwordx4 v[22:23], v[2:5], off nt
	s_nop 1
	v_cvt_pk_bf16_f32 v2, v9, v7
	v_ashrrev_i32_e32 v7, 31, v6
	v_cvt_pk_bf16_f32 v3, v11, v13
	v_cvt_pk_bf16_f32 v4, v15, v17
	v_cvt_pk_bf16_f32 v5, v19, v21
	v_lshlrev_b64 v[6:7], 10, v[6:7]
	ds_read2_b32 v[8:9], v122 offset0:49 offset1:57
	ds_read2_b32 v[10:11], v122 offset0:16 offset1:24
	ds_read2_b32 v[12:13], v122 offset0:82 offset1:90
	ds_read2_b32 v[14:15], v122 offset0:115 offset1:123
	ds_read2_b32 v[16:17], v122 offset0:148 offset1:156
	ds_read2_b32 v[18:19], v122 offset0:181 offset1:189
	ds_read2_b32 v[20:21], v122 offset0:214 offset1:222
	ds_read2_b32 v[22:23], v122 offset0:247 offset1:255
	v_lshl_add_u64 v[6:7], v[132:133], 0, v[6:7]
	global_store_dwordx4 v[6:7], v[2:5], off nt
	v_add_u32_e32 v6, s2, v120
	v_ashrrev_i32_e32 v7, 31, v6
	v_lshlrev_b64 v[6:7], 10, v[6:7]
	s_waitcnt lgkmcnt(6)
	v_cvt_pk_bf16_f32 v2, v10, v8
	s_waitcnt lgkmcnt(4)
	v_cvt_pk_bf16_f32 v3, v12, v14
	s_waitcnt lgkmcnt(2)
	v_cvt_pk_bf16_f32 v4, v16, v18
	s_waitcnt lgkmcnt(0)
	v_cvt_pk_bf16_f32 v5, v20, v22
	v_lshl_add_u64 v[6:7], v[132:133], 0, v[6:7]
	global_store_dwordx4 v[6:7], v[2:5], off nt
	v_add_u32_e32 v6, s2, v121
	v_ashrrev_i32_e32 v7, 31, v6
	v_lshlrev_b64 v[6:7], 10, v[6:7]
	v_cvt_pk_bf16_f32 v2, v11, v9
	v_cvt_pk_bf16_f32 v3, v13, v15
	v_cvt_pk_bf16_f32 v4, v17, v19
	v_cvt_pk_bf16_f32 v5, v21, v23
	v_lshl_add_u64 v[6:7], v[132:133], 0, v[6:7]
	global_store_dwordx4 v[6:7], v[2:5], off nt
	s_waitcnt lgkmcnt(0)

.LBB0_55:
	s_andn2_b64 vcc, exec, s[2:3]
	s_cbranch_vccnz .LBB0_57
	s_and_b32 s2, s90, 0x1ffc0
	s_add_i32 s2, s2, 0xfffed100
	v_add_u32_e32 v2, s2, v1
	v_ashrrev_i32_e32 v3, 31, v2
	v_readlane_b32 s52, v252, 18
	s_and_b32 s8, s22, 0x7e0
	v_lshlrev_b64 v[2:3], 13, v[2:3]
	v_readlane_b32 s54, v252, 20
	v_readlane_b32 s55, v252, 21
	s_lshl_b32 s6, s8, 2
	v_lshlrev_b32_e32 v34, 2, v112
	v_lshl_add_u64 v[2:3], s[54:55], 0, v[2:3]
	v_lshl_add_u64 v[2:3], v[2:3], 0, s[6:7]
	v_lshl_add_u64 v[30:31], v[2:3], 0, v[34:35]
	v_add_co_u32_e32 v6, vcc, s81, v30
	v_add_u32_e32 v34, v115, v118
	s_nop 0
	v_addc_co_u32_e32 v7, vcc, 0, v31, vcc
	v_add_co_u32_e32 v10, vcc, s83, v30
	global_load_dwordx4 v[2:5], v[30:31], off nt
	s_nop 0
	global_load_dwordx4 v[6:9], v[6:7], off nt
	v_addc_co_u32_e32 v11, vcc, 0, v31, vcc
	v_add_co_u32_e32 v14, vcc, s84, v30
	v_add_u32_e32 v134, 0x420, v34
	s_nop 0
	v_addc_co_u32_e32 v15, vcc, 0, v31, vcc
	v_add_co_u32_e32 v18, vcc, s85, v30
	global_load_dwordx4 v[10:13], v[10:11], off nt
	s_nop 0
	global_load_dwordx4 v[14:17], v[14:15], off nt
	v_addc_co_u32_e32 v19, vcc, 0, v31, vcc
	v_add_co_u32_e32 v22, vcc, s86, v30
	v_add_u32_e32 v135, 0x428, v34
	s_nop 0
	v_addc_co_u32_e32 v23, vcc, 0, v31, vcc
	global_load_dwordx4 v[18:21], v[18:19], off nt
	s_nop 0
	global_load_dwordx4 v[22:25], v[22:23], off nt
	v_add_co_u32_e32 v26, vcc, s87, v30
	v_add_u32_e32 v136, 0x840, v34
	s_nop 0
	v_addc_co_u32_e32 v27, vcc, 0, v31, vcc
	global_load_dwordx4 v[26:29], v[26:27], off nt
	v_add_co_u32_e32 v30, vcc, s88, v30
	v_add_u32_e32 v137, 0x848, v34
	s_nop 0
	v_addc_co_u32_e32 v31, vcc, 0, v31, vcc
	global_load_dwordx4 v[30:33], v[30:31], off nt
	v_add_u32_e32 v138, 0xc60, v34
	v_add_u32_e32 v139, 0xc68, v34
	v_add_u32_e32 v140, 0x1080, v34
	v_add_u32_e32 v141, 0x1088, v34
	v_add_u32_e32 v142, 0x14a0, v34
	v_add_u32_e32 v143, 0x14a8, v34
	v_add_u32_e32 v144, 0x18c0, v34
	v_add_u32_e32 v145, 0x18c8, v34
	v_add_u32_e32 v146, 0x1ce0, v34
	v_add_u32_e32 v147, 0x1ce8, v34
	v_add_u32_e32 v116, s8, v1
	s_mov_b32 s3, s7
	v_ashrrev_i32_e32 v117, 31, v116
	v_lshl_add_u64 v[132:133], s[2:3], 1, v[66:67]
	v_lshlrev_b64 v[116:117], 12, v[116:117]
	v_readlane_b32 s53, v252, 19
	v_readlane_b32 s56, v252, 22
	v_readlane_b32 s57, v252, 23
	v_readlane_b32 s58, v252, 24
	v_readlane_b32 s59, v252, 25
	v_readlane_b32 s60, v252, 26
	v_readlane_b32 s61, v252, 27
	v_readlane_b32 s62, v252, 28
	v_readlane_b32 s63, v252, 29
	v_readlane_b32 s64, v252, 30
	v_readlane_b32 s65, v252, 31
	v_readlane_b32 s66, v252, 32
	v_readlane_b32 s67, v252, 33
	s_waitcnt vmcnt(7)
	ds_write2_b32 v34, v2, v3 offset1:1
	ds_write2_b32 v34, v4, v5 offset0:2 offset1:3
	s_waitcnt vmcnt(6)
	ds_write2_b32 v134, v6, v7 offset1:1
	ds_write2_b32 v135, v8, v9 offset1:1
	s_waitcnt vmcnt(5)
	ds_write2_b32 v136, v10, v11 offset1:1
	ds_write2_b32 v137, v12, v13 offset1:1
	s_waitcnt vmcnt(4)
	ds_write2_b32 v138, v14, v15 offset1:1
	ds_write2_b32 v139, v16, v17 offset1:1
	s_waitcnt vmcnt(3)
	ds_write2_b32 v140, v18, v19 offset1:1
	ds_write2_b32 v141, v20, v21 offset1:1
	s_waitcnt vmcnt(2)
	ds_write2_b32 v142, v22, v23 offset1:1
	ds_write2_b32 v143, v24, v25 offset1:1
	s_waitcnt vmcnt(1)
	ds_write2_b32 v144, v26, v27 offset1:1
	ds_write2_b32 v145, v28, v29 offset1:1
	s_waitcnt vmcnt(0)
	ds_write2_b32 v146, v30, v31 offset1:1
	ds_write2_b32 v147, v32, v33 offset1:1
	s_waitcnt lgkmcnt(0)
	ds_read2_b32 v[6:7], v122 offset0:33 offset1:41
	ds_read2_b32 v[8:9], v122 offset1:8
	ds_read2_b32 v[10:11], v122 offset0:66 offset1:74
	ds_read2_b32 v[12:13], v122 offset0:99 offset1:107
	ds_read2_b32 v[14:15], v122 offset0:132 offset1:140
	ds_read2_b32 v[16:17], v122 offset0:165 offset1:173
	ds_read2_b32 v[18:19], v122 offset0:198 offset1:206
	ds_read2_b32 v[20:21], v122 offset0:231 offset1:239
	v_lshl_add_u64 v[22:23], v[132:133], 0, v[116:117]
	s_waitcnt lgkmcnt(6)
	v_cvt_pk_bf16_f32 v2, v8, v6
	s_waitcnt lgkmcnt(4)
	v_cvt_pk_bf16_f32 v3, v10, v12
	s_waitcnt lgkmcnt(2)
	v_cvt_pk_bf16_f32 v4, v14, v16
	s_waitcnt lgkmcnt(0)
	v_cvt_pk_bf16_f32 v5, v18, v20
	global_store_dwordx4 v[22:23], v[2:5], off nt
	v_cvt_pk_bf16_f32 v6, v9, v7
	v_cvt_pk_bf16_f32 v7, v11, v13
	v_add_u32_e32 v2, s8, v119
	v_ashrrev_i32_e32 v3, 31, v2
	v_cvt_pk_bf16_f32 v8, v15, v17
	v_cvt_pk_bf16_f32 v9, v19, v21
	v_lshlrev_b64 v[2:3], 12, v[2:3]
	ds_read2_b32 v[10:11], v122 offset0:49 offset1:57
	ds_read2_b32 v[12:13], v122 offset0:16 offset1:24
	ds_read2_b32 v[14:15], v122 offset0:82 offset1:90
	ds_read2_b32 v[16:17], v122 offset0:115 offset1:123
	ds_read2_b32 v[18:19], v122 offset0:148 offset1:156
	ds_read2_b32 v[20:21], v122 offset0:181 offset1:189
	ds_read2_b32 v[22:23], v122 offset0:214 offset1:222
	ds_read2_b32 v[24:25], v122 offset0:247 offset1:255
	v_lshl_add_u64 v[2:3], v[132:133], 0, v[2:3]
	global_store_dwordx4 v[2:3], v[6:9], off nt
	s_waitcnt lgkmcnt(6)
	v_cvt_pk_bf16_f32 v2, v12, v10
	s_waitcnt lgkmcnt(4)
	v_cvt_pk_bf16_f32 v3, v14, v16
	v_add_u32_e32 v6, s8, v120
	v_ashrrev_i32_e32 v7, 31, v6
	v_lshlrev_b64 v[6:7], 12, v[6:7]
	s_waitcnt lgkmcnt(2)
	v_cvt_pk_bf16_f32 v4, v18, v20
	s_waitcnt lgkmcnt(0)
	v_cvt_pk_bf16_f32 v5, v22, v24
	v_lshl_add_u64 v[6:7], v[132:133], 0, v[6:7]
	global_store_dwordx4 v[6:7], v[2:5], off nt
	v_add_u32_e32 v6, s8, v121
	v_ashrrev_i32_e32 v7, 31, v6
	v_lshlrev_b64 v[6:7], 12, v[6:7]
	v_cvt_pk_bf16_f32 v2, v13, v11
	v_cvt_pk_bf16_f32 v3, v15, v17
	v_cvt_pk_bf16_f32 v4, v19, v21
	v_cvt_pk_bf16_f32 v5, v23, v25
	v_lshl_add_u64 v[6:7], v[132:133], 0, v[6:7]
	global_store_dwordx4 v[6:7], v[2:5], off nt
	s_waitcnt lgkmcnt(0)

.LBB0_58:
	s_andn2_b64 vcc, exec, s[2:3]
	s_cbranch_vccnz .LBB0_76
	s_add_i32 s2, s90, 0xdd00
	s_and_b32 s3, s2, 0xffff
	s_mul_i32 s3, s3, 0xaaab
	s_lshr_b32 s6, s3, 16
	s_lshr_b32 s3, s3, 22
	s_mulk_i32 s3, 0x60
	s_sub_i32 s2, s2, s3
	s_lshl_b32 s11, s2, 5
	s_and_b32 s10, s6, 0xffc0
	s_and_b32 s26, s2, 0xffff
	s_cmpk_lt_u32 s26, 0x5a
	s_cselect_b64 s[8:9], -1, 0
	s_and_b64 s[2:3], s[8:9], exec
	s_cselect_b32 s2, s11, 0
	v_readlane_b32 s52, v252, 18
	s_and_b32 s2, s2, 0x7fe0
	v_readlane_b32 s53, v252, 19
	s_lshl_b32 s6, s2, 2
	v_add_u32_e32 v4, s10, v1
	v_mov_b64_e32 v[2:3], s[52:53]
	s_movk_i32 s2, 0x2d00
	v_mad_i64_i32 v[2:3], s[2:3], v4, s2, v[2:3]
	v_lshl_add_u64 v[2:3], v[2:3], 0, s[6:7]
	v_lshlrev_b32_e32 v34, 2, v112
	s_cmpk_gt_u32 s26, 0x59
	v_lshl_add_u64 v[116:117], v[2:3], 0, v[34:35]
	v_mov_b32_e32 v6, 0
	v_mov_b32_e32 v2, 0
	v_mov_b32_e32 v3, 0
	v_mov_b32_e32 v4, 0
	v_mov_b32_e32 v5, 0
	v_readlane_b32 s54, v252, 20
	v_readlane_b32 s55, v252, 21
	v_readlane_b32 s56, v252, 22
	v_readlane_b32 s57, v252, 23
	v_readlane_b32 s58, v252, 24
	v_readlane_b32 s59, v252, 25
	v_readlane_b32 s60, v252, 26
	v_readlane_b32 s61, v252, 27
	v_readlane_b32 s62, v252, 28
	v_readlane_b32 s63, v252, 29
	v_readlane_b32 s64, v252, 30
	v_readlane_b32 s65, v252, 31
	v_readlane_b32 s66, v252, 32
	v_readlane_b32 s67, v252, 33
	s_cbranch_scc1 .LBB0_61
	global_load_dwordx4 v[2:5], v[116:117], off nt
.LBB0_61:
	v_cndmask_b32_e64 v7, 0, 1, s[8:9]
	v_cmp_ne_u32_e64 s[2:3], 1, v7
	s_andn2_b64 vcc, exec, s[8:9]
	v_mov_b32_e32 v7, 0
	v_mov_b32_e32 v8, 0
	v_mov_b32_e32 v9, 0
	s_cbranch_vccnz .LBB0_63
	v_add_co_u32_e32 v6, vcc, 0x16000, v116
	s_nop 1
	v_addc_co_u32_e32 v7, vcc, 0, v117, vcc
	global_load_dwordx4 v[6:9], v[6:7], off offset:2048 nt
.LBB0_63:
	v_mov_b32_e32 v10, 0
	s_and_b64 vcc, exec, s[2:3]
	v_mov_b32_e32 v14, 0
	v_mov_b32_e32 v15, 0
	v_mov_b32_e32 v16, 0
	v_mov_b32_e32 v17, 0
	s_cbranch_vccnz .LBB0_65
	v_add_co_u32_e32 v12, vcc, 0x2d000, v116
	s_nop 1
	v_addc_co_u32_e32 v13, vcc, 0, v117, vcc
	global_load_dwordx4 v[14:17], v[12:13], off nt
.LBB0_65:
	s_and_b64 vcc, exec, s[2:3]
	v_mov_b32_e32 v11, 0
	v_mov_b32_e32 v12, 0
	v_mov_b32_e32 v13, 0
	s_cbranch_vccnz .LBB0_67
	v_add_co_u32_e32 v10, vcc, 0x43000, v116
	s_nop 1
	v_addc_co_u32_e32 v11, vcc, 0, v117, vcc
	global_load_dwordx4 v[10:13], v[10:11], off offset:2048 nt
.LBB0_67:
	v_mov_b32_e32 v18, 0
	s_and_b64 vcc, exec, s[2:3]
	v_mov_b32_e32 v22, 0
	v_mov_b32_e32 v23, 0
	v_mov_b32_e32 v24, 0
	v_mov_b32_e32 v25, 0
	s_cbranch_vccnz .LBB0_69
	v_add_co_u32_e32 v20, vcc, 0x5a000, v116
	s_nop 1
	v_addc_co_u32_e32 v21, vcc, 0, v117, vcc
	global_load_dwordx4 v[22:25], v[20:21], off nt
.LBB0_69:
	s_and_b64 vcc, exec, s[2:3]
	v_mov_b32_e32 v19, 0
	v_mov_b32_e32 v20, 0
	v_mov_b32_e32 v21, 0
	s_cbranch_vccnz .LBB0_71
	v_add_co_u32_e32 v18, vcc, 0x70000, v116
	s_nop 1
	v_addc_co_u32_e32 v19, vcc, 0, v117, vcc
	global_load_dwordx4 v[18:21], v[18:19], off offset:2048 nt
.LBB0_71:
	v_mov_b32_e32 v26, 0
	s_and_b64 vcc, exec, s[2:3]
	v_mov_b32_e32 v30, 0
	v_mov_b32_e32 v31, 0
	v_mov_b32_e32 v32, 0
	v_mov_b32_e32 v33, 0
	s_cbranch_vccnz .LBB0_73
	v_add_co_u32_e32 v28, vcc, 0x87000, v116
	s_nop 1
	v_addc_co_u32_e32 v29, vcc, 0, v117, vcc
	global_load_dwordx4 v[30:33], v[28:29], off nt
.LBB0_73:
	s_and_b64 vcc, exec, s[2:3]
	v_mov_b32_e32 v27, 0
	v_mov_b32_e32 v28, 0
	v_mov_b32_e32 v29, 0
	s_cbranch_vccnz .LBB0_75
	v_add_co_u32_e32 v26, vcc, 0x9d000, v116
	s_nop 1
	v_addc_co_u32_e32 v27, vcc, 0, v117, vcc
	global_load_dwordx4 v[26:29], v[26:27], off offset:2048 nt
.LBB0_75:
	v_add_u32_e32 v34, v115, v118
	s_waitcnt vmcnt(0)
	ds_write2_b32 v34, v2, v3 offset1:1
	ds_write2_b32 v34, v4, v5 offset0:2 offset1:3
	v_add_u32_e32 v2, 0x420, v34
	ds_write2_b32 v2, v6, v7 offset1:1
	v_add_u32_e32 v2, 0x428, v34
	ds_write2_b32 v2, v8, v9 offset1:1
	v_add_u32_e32 v2, 0x840, v34
	ds_write2_b32 v2, v14, v15 offset1:1
	v_add_u32_e32 v2, 0x848, v34
	ds_write2_b32 v2, v16, v17 offset1:1
	v_add_u32_e32 v2, 0xc60, v34
	ds_write2_b32 v2, v10, v11 offset1:1
	v_add_u32_e32 v2, 0xc68, v34
	ds_write2_b32 v2, v12, v13 offset1:1
	v_add_u32_e32 v2, 0x1080, v34
	ds_write2_b32 v2, v22, v23 offset1:1
	v_add_u32_e32 v2, 0x1088, v34
	ds_write2_b32 v2, v24, v25 offset1:1
	v_add_u32_e32 v2, 0x14a0, v34
	ds_write2_b32 v2, v18, v19 offset1:1
	v_add_u32_e32 v2, 0x14a8, v34
	ds_write2_b32 v2, v20, v21 offset1:1
	v_add_u32_e32 v2, 0x18c0, v34
	ds_write2_b32 v2, v30, v31 offset1:1
	v_add_u32_e32 v2, 0x18c8, v34
	ds_write2_b32 v2, v32, v33 offset1:1
	v_add_u32_e32 v2, 0x1ce0, v34
	ds_write2_b32 v2, v26, v27 offset1:1
	v_add_u32_e32 v2, 0x1ce8, v34
	ds_write2_b32 v2, v28, v29 offset1:1
	s_waitcnt lgkmcnt(0)
	ds_read2_b32 v[6:7], v122 offset0:33 offset1:41
	ds_read2_b32 v[8:9], v122 offset1:8
	ds_read2_b32 v[10:11], v122 offset0:66 offset1:74
	ds_read2_b32 v[12:13], v122 offset0:99 offset1:107
	ds_read2_b32 v[14:15], v122 offset0:132 offset1:140
	ds_read2_b32 v[16:17], v122 offset0:165 offset1:173
	ds_read2_b32 v[18:19], v122 offset0:198 offset1:206
	ds_read2_b32 v[20:21], v122 offset0:231 offset1:239
	s_and_b32 s2, 0xffff, s11
	s_and_b32 s3, 0xffff, s10
	v_add_u32_e32 v24, s2, v1
	s_lshl_b32 s6, s3, 1
	v_ashrrev_i32_e32 v25, 31, v24
	v_lshl_add_u64 v[22:23], v[68:69], 0, s[6:7]
	v_lshlrev_b64 v[24:25], 12, v[24:25]
	s_waitcnt lgkmcnt(6)
	v_cvt_pk_bf16_f32 v2, v8, v6
	s_waitcnt lgkmcnt(4)
	v_cvt_pk_bf16_f32 v3, v10, v12
	s_waitcnt lgkmcnt(2)
	v_cvt_pk_bf16_f32 v4, v14, v16
	s_waitcnt lgkmcnt(0)
	v_cvt_pk_bf16_f32 v5, v18, v20
	v_lshl_add_u64 v[24:25], v[22:23], 0, v[24:25]
	v_add_u32_e32 v6, s2, v119
	global_store_dwordx4 v[24:25], v[2:5], off nt
	s_nop 1
	v_cvt_pk_bf16_f32 v2, v9, v7
	v_ashrrev_i32_e32 v7, 31, v6
	v_cvt_pk_bf16_f32 v3, v11, v13
	v_cvt_pk_bf16_f32 v4, v15, v17
	v_cvt_pk_bf16_f32 v5, v19, v21
	v_lshlrev_b64 v[6:7], 12, v[6:7]
	ds_read2_b32 v[8:9], v122 offset0:49 offset1:57
	ds_read2_b32 v[10:11], v122 offset0:16 offset1:24
	ds_read2_b32 v[12:13], v122 offset0:82 offset1:90
	ds_read2_b32 v[14:15], v122 offset0:115 offset1:123
	ds_read2_b32 v[16:17], v122 offset0:148 offset1:156
	ds_read2_b32 v[18:19], v122 offset0:181 offset1:189
	ds_read2_b32 v[20:21], v122 offset0:214 offset1:222
	ds_read2_b32 v[24:25], v122 offset0:247 offset1:255
	v_lshl_add_u64 v[6:7], v[22:23], 0, v[6:7]
	global_store_dwordx4 v[6:7], v[2:5], off nt
	v_add_u32_e32 v6, s2, v120
	v_ashrrev_i32_e32 v7, 31, v6
	v_lshlrev_b64 v[6:7], 12, v[6:7]
	s_waitcnt lgkmcnt(6)
	v_cvt_pk_bf16_f32 v2, v10, v8
	s_waitcnt lgkmcnt(4)
	v_cvt_pk_bf16_f32 v3, v12, v14
	s_waitcnt lgkmcnt(2)
	v_cvt_pk_bf16_f32 v4, v16, v18
	s_waitcnt lgkmcnt(0)
	v_cvt_pk_bf16_f32 v5, v20, v24
	v_lshl_add_u64 v[6:7], v[22:23], 0, v[6:7]
	global_store_dwordx4 v[6:7], v[2:5], off nt
	v_add_u32_e32 v6, s2, v121
	v_ashrrev_i32_e32 v7, 31, v6
	v_lshlrev_b64 v[6:7], 12, v[6:7]
	v_cvt_pk_bf16_f32 v2, v11, v9
	v_cvt_pk_bf16_f32 v3, v13, v15
	v_cvt_pk_bf16_f32 v4, v17, v19
	v_cvt_pk_bf16_f32 v5, v21, v25
	v_lshl_add_u64 v[6:7], v[22:23], 0, v[6:7]
	global_store_dwordx4 v[6:7], v[2:5], off nt
	s_waitcnt lgkmcnt(0)

.LBB0_77:
	s_andn2_b64 vcc, exec, s[2:3]
	s_cbranch_vccnz .LBB0_79
	s_and_b32 s2, s90, 0x1ffc0
	s_add_i32 s2, s2, 0xfffee500
	v_add_u32_e32 v2, s2, v1
	v_ashrrev_i32_e32 v3, 31, v2
	s_and_b32 s8, s22, 0x7e0
	v_lshlrev_b64 v[2:3], 13, v[2:3]
	v_lshl_add_u64 v[2:3], s[42:43], 0, v[2:3]
	s_lshl_b32 s6, s8, 2
	v_lshl_add_u64 v[2:3], v[2:3], 0, s[6:7]
	v_lshlrev_b32_e32 v34, 2, v112
	v_lshl_add_u64 v[30:31], v[2:3], 0, v[34:35]
	v_add_co_u32_e32 v6, vcc, s81, v30
	v_add_u32_e32 v34, v115, v118
	s_nop 0
	v_addc_co_u32_e32 v7, vcc, 0, v31, vcc
	v_add_co_u32_e32 v10, vcc, s83, v30
	global_load_dwordx4 v[2:5], v[30:31], off nt
	s_nop 0
	global_load_dwordx4 v[6:9], v[6:7], off nt
	v_addc_co_u32_e32 v11, vcc, 0, v31, vcc
	v_add_co_u32_e32 v14, vcc, s84, v30
	v_add_u32_e32 v134, 0x420, v34
	s_nop 0
	v_addc_co_u32_e32 v15, vcc, 0, v31, vcc
	v_add_co_u32_e32 v18, vcc, s85, v30
	global_load_dwordx4 v[10:13], v[10:11], off nt
	s_nop 0
	global_load_dwordx4 v[14:17], v[14:15], off nt
	v_addc_co_u32_e32 v19, vcc, 0, v31, vcc
	v_add_co_u32_e32 v22, vcc, s86, v30
	v_add_u32_e32 v135, 0x428, v34
	s_nop 0
	v_addc_co_u32_e32 v23, vcc, 0, v31, vcc
	global_load_dwordx4 v[18:21], v[18:19], off nt
	s_nop 0
	global_load_dwordx4 v[22:25], v[22:23], off nt
	v_add_co_u32_e32 v26, vcc, s87, v30
	v_add_u32_e32 v136, 0x840, v34
	s_nop 0
	v_addc_co_u32_e32 v27, vcc, 0, v31, vcc
	global_load_dwordx4 v[26:29], v[26:27], off nt
	v_add_co_u32_e32 v30, vcc, s88, v30
	v_add_u32_e32 v137, 0x848, v34
	s_nop 0
	v_addc_co_u32_e32 v31, vcc, 0, v31, vcc
	global_load_dwordx4 v[30:33], v[30:31], off nt
	v_add_u32_e32 v138, 0xc60, v34
	v_add_u32_e32 v139, 0xc68, v34
	v_add_u32_e32 v140, 0x1080, v34
	v_add_u32_e32 v141, 0x1088, v34
	v_add_u32_e32 v142, 0x14a0, v34
	v_add_u32_e32 v143, 0x14a8, v34
	v_add_u32_e32 v144, 0x18c0, v34
	v_add_u32_e32 v145, 0x18c8, v34
	v_add_u32_e32 v146, 0x1ce0, v34
	v_add_u32_e32 v147, 0x1ce8, v34
	v_add_u32_e32 v116, s8, v1
	s_mov_b32 s3, s7
	v_ashrrev_i32_e32 v117, 31, v116
	v_lshl_add_u64 v[132:133], s[2:3], 1, v[70:71]
	v_lshlrev_b64 v[116:117], 12, v[116:117]
	s_waitcnt vmcnt(7)
	ds_write2_b32 v34, v2, v3 offset1:1
	ds_write2_b32 v34, v4, v5 offset0:2 offset1:3
	s_waitcnt vmcnt(6)
	ds_write2_b32 v134, v6, v7 offset1:1
	ds_write2_b32 v135, v8, v9 offset1:1
	s_waitcnt vmcnt(5)
	ds_write2_b32 v136, v10, v11 offset1:1
	ds_write2_b32 v137, v12, v13 offset1:1
	s_waitcnt vmcnt(4)
	ds_write2_b32 v138, v14, v15 offset1:1
	ds_write2_b32 v139, v16, v17 offset1:1
	s_waitcnt vmcnt(3)
	ds_write2_b32 v140, v18, v19 offset1:1
	ds_write2_b32 v141, v20, v21 offset1:1
	s_waitcnt vmcnt(2)
	ds_write2_b32 v142, v22, v23 offset1:1
	ds_write2_b32 v143, v24, v25 offset1:1
	s_waitcnt vmcnt(1)
	ds_write2_b32 v144, v26, v27 offset1:1
	ds_write2_b32 v145, v28, v29 offset1:1
	s_waitcnt vmcnt(0)
	ds_write2_b32 v146, v30, v31 offset1:1
	ds_write2_b32 v147, v32, v33 offset1:1
	s_waitcnt lgkmcnt(0)
	ds_read2_b32 v[6:7], v122 offset0:33 offset1:41
	ds_read2_b32 v[8:9], v122 offset1:8
	ds_read2_b32 v[10:11], v122 offset0:66 offset1:74
	ds_read2_b32 v[12:13], v122 offset0:99 offset1:107
	ds_read2_b32 v[14:15], v122 offset0:132 offset1:140
	ds_read2_b32 v[16:17], v122 offset0:165 offset1:173
	ds_read2_b32 v[18:19], v122 offset0:198 offset1:206
	ds_read2_b32 v[20:21], v122 offset0:231 offset1:239
	v_lshl_add_u64 v[22:23], v[132:133], 0, v[116:117]
	s_waitcnt lgkmcnt(6)
	v_cvt_pk_bf16_f32 v2, v8, v6
	s_waitcnt lgkmcnt(4)
	v_cvt_pk_bf16_f32 v3, v10, v12
	s_waitcnt lgkmcnt(2)
	v_cvt_pk_bf16_f32 v4, v14, v16
	s_waitcnt lgkmcnt(0)
	v_cvt_pk_bf16_f32 v5, v18, v20
	global_store_dwordx4 v[22:23], v[2:5], off nt
	v_cvt_pk_bf16_f32 v6, v9, v7
	v_cvt_pk_bf16_f32 v7, v11, v13
	v_add_u32_e32 v2, s8, v119
	v_ashrrev_i32_e32 v3, 31, v2
	v_cvt_pk_bf16_f32 v8, v15, v17
	v_cvt_pk_bf16_f32 v9, v19, v21
	v_lshlrev_b64 v[2:3], 12, v[2:3]
	ds_read2_b32 v[10:11], v122 offset0:49 offset1:57
	ds_read2_b32 v[12:13], v122 offset0:16 offset1:24
	ds_read2_b32 v[14:15], v122 offset0:82 offset1:90
	ds_read2_b32 v[16:17], v122 offset0:115 offset1:123
	ds_read2_b32 v[18:19], v122 offset0:148 offset1:156
	ds_read2_b32 v[20:21], v122 offset0:181 offset1:189
	ds_read2_b32 v[22:23], v122 offset0:214 offset1:222
	ds_read2_b32 v[24:25], v122 offset0:247 offset1:255
	v_lshl_add_u64 v[2:3], v[132:133], 0, v[2:3]
	global_store_dwordx4 v[2:3], v[6:9], off nt
	s_waitcnt lgkmcnt(6)
	v_cvt_pk_bf16_f32 v2, v12, v10
	s_waitcnt lgkmcnt(4)
	v_cvt_pk_bf16_f32 v3, v14, v16
	v_add_u32_e32 v6, s8, v120
	v_ashrrev_i32_e32 v7, 31, v6
	v_lshlrev_b64 v[6:7], 12, v[6:7]
	s_waitcnt lgkmcnt(2)
	v_cvt_pk_bf16_f32 v4, v18, v20
	s_waitcnt lgkmcnt(0)
	v_cvt_pk_bf16_f32 v5, v22, v24
	v_lshl_add_u64 v[6:7], v[132:133], 0, v[6:7]
	global_store_dwordx4 v[6:7], v[2:5], off nt
	v_add_u32_e32 v6, s8, v121
	v_ashrrev_i32_e32 v7, 31, v6
	v_lshlrev_b64 v[6:7], 12, v[6:7]
	v_cvt_pk_bf16_f32 v2, v13, v11
	v_cvt_pk_bf16_f32 v3, v15, v17
	v_cvt_pk_bf16_f32 v4, v19, v21
	v_cvt_pk_bf16_f32 v5, v23, v25
	v_lshl_add_u64 v[6:7], v[132:133], 0, v[6:7]
	global_store_dwordx4 v[6:7], v[2:5], off nt
	s_waitcnt lgkmcnt(0)

.LBB0_80:
	s_andn2_b64 vcc, exec, s[2:3]
	s_cbranch_vccnz .LBB0_114
	s_add_i32 s2, s90, 0xfe00
	s_bfe_u32 s3, s2, 0xd0003
	s_mulk_i32 s3, 0x147b
	s_lshr_b32 s6, s3, 17
	s_mul_i32 s3, s6, 0xc8
	s_sub_i32 s8, s2, s3
	s_and_b32 s2, s8, 0xffff
	s_lshl_b32 s34, s2, 5
	v_or_b32_e32 v2, s34, v123
	s_cmp_lt_u32 s2, 32
	v_lshrrev_b32_e32 v3, 1, v2
	s_cselect_b64 s[2:3], -1, 0
	s_and_b32 s8, s8, 0xe0
	v_and_b32_e32 v3, 60, v3
	s_cmpk_eq_i32 s8, 0x60
	v_or_b32_e32 v4, v3, v113
	v_add_u32_e32 v3, v124, v3
	s_cselect_b64 s[8:9], -1, 0
	s_and_b32 s10, s34, 0x1f80
	v_cndmask_b32_e64 v3, v3, v4, s[0:1]
	v_or_b32_e32 v3, s10, v3
	s_or_b64 vcc, s[2:3], s[8:9]
	s_movk_i32 s2, 0x1810
	v_cndmask_b32_e32 v3, v2, v3, vcc
	v_cmp_gt_u32_e32 vcc, s2, v2
	s_mul_i32 s2, s6, 0x181000
	s_add_u32 s10, s40, s2
	v_cndmask_b32_e32 v2, -1, v3, vcc
	s_addc_u32 s11, s41, 0
	v_cmp_gt_i32_e32 vcc, 0, v2
	v_cmp_lt_i32_e64 s[2:3], -1, v2
	v_add_u32_e32 v4, v125, v126
	s_and_saveexec_b64 s[8:9], vcc
	s_xor_b64 s[8:9], exec, s[8:9]
	ds_write2_b32 v4, v35, v35 offset1:66
	s_or_saveexec_b64 s[8:9], s[8:9]
	v_cndmask_b32_e64 v34, 0, v2, s[2:3]
	v_lshl_add_u64 v[2:3], v[34:35], 2, s[10:11]
	v_mov_b32_e32 v5, 0
	v_mov_b32_e32 v6, 0
	s_xor_b64 exec, exec, s[8:9]
	s_cbranch_execz .LBB0_85
	v_lshl_add_u64 v[6:7], v[2:3], 0, v[36:37]
	v_lshl_add_u64 v[8:9], v[2:3], 0, v[38:39]
	v_lshl_add_u64 v[10:11], v[2:3], 0, v[40:41]
	v_lshl_add_u64 v[12:13], v[2:3], 0, v[42:43]
	global_load_dword v7, v[6:7], off nt
	s_nop 0
	global_load_dword v8, v[8:9], off nt
	s_nop 0
	global_load_dword v5, v[10:11], off nt
	global_load_dword v6, v[12:13], off nt
	s_waitcnt vmcnt(2)
	ds_write2_b32 v4, v7, v8 offset1:66
.LBB0_85:
	s_or_b64 exec, exec, s[8:9]
	s_waitcnt vmcnt(0)
	ds_write2_b32 v128, v5, v6 offset1:66
	s_and_saveexec_b64 s[2:3], vcc
	s_xor_b64 s[2:3], exec, s[2:3]
	ds_write2_b32 v130, v35, v35 offset1:66
	s_or_saveexec_b64 s[2:3], s[2:3]
	v_mov_b32_e32 v4, 0
	v_mov_b32_e32 v5, 0
	s_xor_b64 exec, exec, s[2:3]
	s_cbranch_execz .LBB0_89
	v_lshl_add_u64 v[4:5], v[2:3], 0, v[44:45]
	v_lshl_add_u64 v[6:7], v[2:3], 0, v[46:47]
	v_lshl_add_u64 v[8:9], v[2:3], 0, v[48:49]
	v_lshl_add_u64 v[10:11], v[2:3], 0, v[50:51]
	global_load_dword v12, v[4:5], off nt
	s_nop 0
	global_load_dword v6, v[6:7], off nt
	s_nop 0
	global_load_dword v4, v[8:9], off nt
	global_load_dword v5, v[10:11], off nt
	s_waitcnt vmcnt(2)
	ds_write2_b32 v130, v12, v6 offset1:66
.LBB0_89:
	s_or_b64 exec, exec, s[2:3]
	s_waitcnt vmcnt(0)
	ds_write2_b32 v129, v4, v5 offset1:66
	s_and_saveexec_b64 s[2:3], vcc
	s_xor_b64 s[2:3], exec, s[2:3]
	ds_write2_b32 v131, v35, v35 offset1:66
	s_or_saveexec_b64 s[2:3], s[2:3]
	v_mov_b32_e32 v4, 0
	v_mov_b32_e32 v5, 0
	s_xor_b64 exec, exec, s[2:3]
	s_cbranch_execz .LBB0_93
	v_lshl_add_u64 v[4:5], v[2:3], 0, v[52:53]
	v_lshl_add_u64 v[6:7], v[2:3], 0, v[54:55]
	v_lshl_add_u64 v[8:9], v[2:3], 0, v[56:57]
	v_lshl_add_u64 v[10:11], v[2:3], 0, v[58:59]
	global_load_dword v12, v[4:5], off nt
	s_nop 0
	global_load_dword v6, v[6:7], off nt
	s_nop 0
	global_load_dword v4, v[8:9], off nt
	global_load_dword v5, v[10:11], off nt
	s_waitcnt vmcnt(2)
	ds_write2_b32 v131, v12, v6 offset1:66
.LBB0_93:
	s_or_b64 exec, exec, s[2:3]
	s_waitcnt vmcnt(0)
	ds_write2_b32 v131, v4, v5 offset0:132 offset1:198
	v_add_u32_e32 v4, 0x400, v131
	s_and_saveexec_b64 s[2:3], vcc
	s_xor_b64 s[2:3], exec, s[2:3]
	ds_write2_b32 v4, v35, v35 offset0:8 offset1:74
	s_or_saveexec_b64 s[2:3], s[2:3]
	v_mov_b32_e32 v5, 0
	v_mov_b32_e32 v6, 0
	s_xor_b64 exec, exec, s[2:3]
	s_cbranch_execz .LBB0_97
	v_lshl_add_u64 v[6:7], v[2:3], 0, v[60:61]
	v_lshl_add_u64 v[8:9], v[2:3], 0, v[74:75]
	v_lshl_add_u64 v[10:11], v[2:3], 0, v[76:77]
	v_lshl_add_u64 v[12:13], v[2:3], 0, v[78:79]
	global_load_dword v7, v[6:7], off nt
	s_nop 0
	global_load_dword v8, v[8:9], off nt
	s_nop 0
	global_load_dword v5, v[10:11], off nt
	global_load_dword v6, v[12:13], off nt
	s_waitcnt vmcnt(2)
	ds_write2_b32 v4, v7, v8 offset0:8 offset1:74
.LBB0_97:
	s_or_b64 exec, exec, s[2:3]
	s_waitcnt vmcnt(0)
	ds_write2_b32 v4, v5, v6 offset0:140 offset1:206
	v_add_u32_e32 v4, 0x800, v131
	s_and_saveexec_b64 s[2:3], vcc
	s_xor_b64 s[2:3], exec, s[2:3]
	ds_write2_b32 v4, v35, v35 offset0:16 offset1:82
	s_or_saveexec_b64 s[2:3], s[2:3]
	v_mov_b32_e32 v5, 0
	v_mov_b32_e32 v6, 0
	s_xor_b64 exec, exec, s[2:3]
	s_cbranch_execz .LBB0_101
	v_lshl_add_u64 v[6:7], v[2:3], 0, v[80:81]
	v_lshl_add_u64 v[8:9], v[2:3], 0, v[82:83]
	v_lshl_add_u64 v[10:11], v[2:3], 0, v[84:85]
	v_lshl_add_u64 v[12:13], v[2:3], 0, v[86:87]
	global_load_dword v7, v[6:7], off nt
	s_nop 0
	global_load_dword v8, v[8:9], off nt
	s_nop 0
	global_load_dword v5, v[10:11], off nt
	global_load_dword v6, v[12:13], off nt
	s_waitcnt vmcnt(2)
	ds_write2_b32 v4, v7, v8 offset0:16 offset1:82
.LBB0_101:
	s_or_b64 exec, exec, s[2:3]
	s_waitcnt vmcnt(0)
	ds_write2_b32 v4, v5, v6 offset0:148 offset1:214
	v_add_u32_e32 v4, 0xc00, v131
	s_and_saveexec_b64 s[2:3], vcc
	s_xor_b64 s[2:3], exec, s[2:3]
	ds_write2_b32 v4, v35, v35 offset0:24 offset1:90
	s_or_saveexec_b64 s[2:3], s[2:3]
	v_mov_b32_e32 v5, 0
	v_mov_b32_e32 v6, 0
	s_xor_b64 exec, exec, s[2:3]
	s_cbranch_execz .LBB0_105
	v_lshl_add_u64 v[6:7], v[2:3], 0, v[88:89]
	v_lshl_add_u64 v[8:9], v[2:3], 0, v[90:91]
	v_lshl_add_u64 v[10:11], v[2:3], 0, v[92:93]
	v_lshl_add_u64 v[12:13], v[2:3], 0, v[94:95]
	global_load_dword v7, v[6:7], off nt
	s_nop 0
	global_load_dword v8, v[8:9], off nt
	s_nop 0
	global_load_dword v5, v[10:11], off nt
	global_load_dword v6, v[12:13], off nt
	s_waitcnt vmcnt(2)
	ds_write2_b32 v4, v7, v8 offset0:24 offset1:90
.LBB0_105:
	s_or_b64 exec, exec, s[2:3]
	s_waitcnt vmcnt(0)
	ds_write2_b32 v4, v5, v6 offset0:156 offset1:222
	v_add_u32_e32 v4, 0x1000, v131
	s_and_saveexec_b64 s[2:3], vcc
	s_xor_b64 s[2:3], exec, s[2:3]
	ds_write2_b32 v4, v35, v35 offset0:32 offset1:98
	s_or_saveexec_b64 s[2:3], s[2:3]
	v_mov_b32_e32 v5, 0
	v_mov_b32_e32 v6, 0
	s_xor_b64 exec, exec, s[2:3]
	s_cbranch_execz .LBB0_109
	v_lshl_add_u64 v[6:7], v[2:3], 0, v[96:97]
	v_lshl_add_u64 v[8:9], v[2:3], 0, v[98:99]
	v_lshl_add_u64 v[10:11], v[2:3], 0, v[100:101]
	v_lshl_add_u64 v[12:13], v[2:3], 0, v[102:103]
	global_load_dword v7, v[6:7], off nt
	s_nop 0
	global_load_dword v8, v[8:9], off nt
	s_nop 0
	global_load_dword v5, v[10:11], off nt
	global_load_dword v6, v[12:13], off nt
	s_waitcnt vmcnt(2)
	ds_write2_b32 v4, v7, v8 offset0:32 offset1:98
.LBB0_109:
	s_or_b64 exec, exec, s[2:3]
	s_waitcnt vmcnt(0)
	ds_write2_b32 v4, v5, v6 offset0:164 offset1:230
	v_add_u32_e32 v4, 0x1400, v131
	s_and_saveexec_b64 s[2:3], vcc
	s_xor_b64 s[2:3], exec, s[2:3]
	ds_write2_b32 v4, v35, v35 offset0:40 offset1:106
	s_or_saveexec_b64 s[2:3], s[2:3]
	v_mov_b32_e32 v5, 0
	v_mov_b32_e32 v6, 0
	s_xor_b64 exec, exec, s[2:3]
	s_cbranch_execz .LBB0_113
	v_lshl_add_u64 v[6:7], v[2:3], 0, v[104:105]
	v_lshl_add_u64 v[8:9], v[2:3], 0, v[106:107]
	v_lshl_add_u64 v[10:11], v[2:3], 0, v[108:109]
	v_lshl_add_u64 v[2:3], v[2:3], 0, v[110:111]
	global_load_dword v7, v[6:7], off nt
	s_nop 0
	global_load_dword v8, v[8:9], off nt
	s_nop 0
	global_load_dword v5, v[10:11], off nt
	global_load_dword v6, v[2:3], off nt
	s_waitcnt vmcnt(2)
	ds_write2_b32 v4, v7, v8 offset0:40 offset1:106
.LBB0_113:
	s_or_b64 exec, exec, s[2:3]
	s_waitcnt vmcnt(0)
	ds_write2_b32 v4, v5, v6 offset0:172 offset1:238
	s_waitcnt lgkmcnt(0)
	ds_read2_b32 v[6:7], v127 offset0:33 offset1:41
	ds_read2_b32 v[8:9], v127 offset1:8
	ds_read2_b32 v[10:11], v127 offset0:66 offset1:74
	ds_read2_b32 v[12:13], v127 offset0:99 offset1:107
	ds_read2_b32 v[14:15], v127 offset0:132 offset1:140
	ds_read2_b32 v[16:17], v127 offset0:165 offset1:173
	ds_read2_b32 v[18:19], v127 offset0:198 offset1:206
	ds_read2_b32 v[20:21], v127 offset0:231 offset1:239
	s_lshl_b32 s2, s6, 6
	v_add_u32_e32 v24, s34, v1
	s_lshl_b32 s6, s2, 1
	v_ashrrev_i32_e32 v25, 31, v24
	v_lshl_add_u64 v[22:23], v[72:73], 0, s[6:7]
	v_lshlrev_b64 v[24:25], 12, v[24:25]
	s_waitcnt lgkmcnt(6)
	v_cvt_pk_bf16_f32 v2, v8, v6
	s_waitcnt lgkmcnt(4)
	v_cvt_pk_bf16_f32 v3, v10, v12
	s_waitcnt lgkmcnt(2)
	v_cvt_pk_bf16_f32 v4, v14, v16
	s_waitcnt lgkmcnt(0)
	v_cvt_pk_bf16_f32 v5, v18, v20
	v_lshl_add_u64 v[24:25], v[22:23], 0, v[24:25]
	v_add_u32_e32 v6, s34, v119
	global_store_dwordx4 v[24:25], v[2:5], off nt
	s_nop 1
	v_cvt_pk_bf16_f32 v2, v9, v7
	v_ashrrev_i32_e32 v7, 31, v6
	v_cvt_pk_bf16_f32 v3, v11, v13
	v_cvt_pk_bf16_f32 v4, v15, v17
	v_cvt_pk_bf16_f32 v5, v19, v21
	v_lshlrev_b64 v[6:7], 12, v[6:7]
	ds_read2_b32 v[8:9], v127 offset0:49 offset1:57
	ds_read2_b32 v[10:11], v127 offset0:16 offset1:24
	ds_read2_b32 v[12:13], v127 offset0:82 offset1:90
	ds_read2_b32 v[14:15], v127 offset0:115 offset1:123
	ds_read2_b32 v[16:17], v127 offset0:148 offset1:156
	ds_read2_b32 v[18:19], v127 offset0:181 offset1:189
	ds_read2_b32 v[20:21], v127 offset0:214 offset1:222
	ds_read2_b32 v[24:25], v127 offset0:247 offset1:255
	v_lshl_add_u64 v[6:7], v[22:23], 0, v[6:7]
	global_store_dwordx4 v[6:7], v[2:5], off nt
	v_add_u32_e32 v6, s34, v120
	v_ashrrev_i32_e32 v7, 31, v6
	v_lshlrev_b64 v[6:7], 12, v[6:7]
	s_waitcnt lgkmcnt(6)
	v_cvt_pk_bf16_f32 v2, v10, v8
	s_waitcnt lgkmcnt(4)
	v_cvt_pk_bf16_f32 v3, v12, v14
	s_waitcnt lgkmcnt(2)
	v_cvt_pk_bf16_f32 v4, v16, v18
	s_waitcnt lgkmcnt(0)
	v_cvt_pk_bf16_f32 v5, v20, v24
	v_lshl_add_u64 v[6:7], v[22:23], 0, v[6:7]
	global_store_dwordx4 v[6:7], v[2:5], off nt
	v_add_u32_e32 v6, s34, v121
	v_ashrrev_i32_e32 v7, 31, v6
	v_lshlrev_b64 v[6:7], 12, v[6:7]
	v_cvt_pk_bf16_f32 v2, v11, v9
	v_cvt_pk_bf16_f32 v3, v13, v15
	v_cvt_pk_bf16_f32 v4, v17, v19
	v_cvt_pk_bf16_f32 v5, v21, v25
	v_lshl_add_u64 v[6:7], v[22:23], 0, v[6:7]
	global_store_dwordx4 v[6:7], v[2:5], off nt
	s_waitcnt lgkmcnt(0)

.LBB0_115:
	s_andn2_b64 vcc, exec, s[2:3]
	s_cbranch_vccnz .LBB0_133
	s_and_b32 s2, s80, 0xffff
	s_mul_hi_u32 s2, s2, 0xbe830
	s_mul_i32 s2, s2, 0xea80
	s_mul_i32 s3, s19, 0xbe83
	s_add_i32 s2, s80, s2
	s_add_i32 s3, s3, 0x694d6880
	s_lshr_b32 s9, s3, 28
	s_sext_i32_i16 s3, s2
	s_lshr_b32 s3, s3, 25
	s_and_b32 s3, s3, 63
	s_add_i32 s3, s2, s3
	s_sext_i32_i16 s6, s3
	s_and_b32 s3, s3, 0xffc0
	s_sub_i32 s2, s2, s3
	s_sext_i32_i16 s26, s2
	s_mul_i32 s2, s9, 0x2b00000
	s_add_u32 s2, s38, s2
	s_addc_u32 s3, s39, 0
	s_and_b32 s8, s6, 0xffffffc0
	s_lshl_b32 s6, s26, 5
	v_add_u32_e32 v2, s8, v1
	v_ashrrev_i32_e32 v3, 31, v2
	s_cmp_gt_i32 s26, -1
	v_lshlrev_b64 v[2:3], 13, v[2:3]
	s_cselect_b64 s[10:11], -1, 0
	v_lshl_add_u64 v[2:3], s[2:3], 0, v[2:3]
	s_and_b64 s[2:3], s[10:11], exec
	s_cselect_b32 s2, s6, 0
	s_cselect_b32 s3, 0, 0
	v_lshl_add_u64 v[2:3], s[2:3], 2, v[2:3]
	v_lshlrev_b32_e32 v34, 2, v112
	s_cmp_lt_i32 s26, 0
	v_lshl_add_u64 v[116:117], v[2:3], 0, v[34:35]
	v_mov_b32_e32 v6, 0
	v_mov_b32_e32 v2, 0
	v_mov_b32_e32 v3, 0
	v_mov_b32_e32 v4, 0
	v_mov_b32_e32 v5, 0
	s_cbranch_scc1 .LBB0_118
	global_load_dwordx4 v[2:5], v[116:117], off nt
.LBB0_118:
	v_cndmask_b32_e64 v7, 0, 1, s[10:11]
	v_cmp_ne_u32_e64 s[2:3], 1, v7
	s_andn2_b64 vcc, exec, s[10:11]
	v_mov_b32_e32 v7, 0
	v_mov_b32_e32 v8, 0
	v_mov_b32_e32 v9, 0
	s_cbranch_vccnz .LBB0_120
	v_add_co_u32_e32 v6, vcc, 0x10000, v116
	s_nop 1
	v_addc_co_u32_e32 v7, vcc, 0, v117, vcc
	global_load_dwordx4 v[6:9], v[6:7], off nt
.LBB0_120:
	v_mov_b32_e32 v10, 0
	s_and_b64 vcc, exec, s[2:3]
	v_mov_b32_e32 v14, 0
	v_mov_b32_e32 v15, 0
	v_mov_b32_e32 v16, 0
	v_mov_b32_e32 v17, 0
	s_cbranch_vccnz .LBB0_122
	v_add_co_u32_e32 v12, vcc, 0x20000, v116
	s_nop 1
	v_addc_co_u32_e32 v13, vcc, 0, v117, vcc
	global_load_dwordx4 v[14:17], v[12:13], off nt
.LBB0_122:
	s_and_b64 vcc, exec, s[2:3]
	v_mov_b32_e32 v11, 0
	v_mov_b32_e32 v12, 0
	v_mov_b32_e32 v13, 0
	s_cbranch_vccnz .LBB0_124
	v_add_co_u32_e32 v10, vcc, 0x30000, v116
	s_nop 1
	v_addc_co_u32_e32 v11, vcc, 0, v117, vcc
	global_load_dwordx4 v[10:13], v[10:11], off nt
.LBB0_124:
	v_mov_b32_e32 v18, 0
	s_and_b64 vcc, exec, s[2:3]
	v_mov_b32_e32 v22, 0
	v_mov_b32_e32 v23, 0
	v_mov_b32_e32 v24, 0
	v_mov_b32_e32 v25, 0
	s_cbranch_vccnz .LBB0_126
	v_add_co_u32_e32 v20, vcc, 0x40000, v116
	s_nop 1
	v_addc_co_u32_e32 v21, vcc, 0, v117, vcc
	global_load_dwordx4 v[22:25], v[20:21], off nt
.LBB0_126:
	s_and_b64 vcc, exec, s[2:3]
	v_mov_b32_e32 v19, 0
	v_mov_b32_e32 v20, 0
	v_mov_b32_e32 v21, 0
	s_cbranch_vccnz .LBB0_128
	v_add_co_u32_e32 v18, vcc, 0x50000, v116
	s_nop 1
	v_addc_co_u32_e32 v19, vcc, 0, v117, vcc
	global_load_dwordx4 v[18:21], v[18:19], off nt
.LBB0_128:
	v_mov_b32_e32 v26, 0
	s_and_b64 vcc, exec, s[2:3]
	v_mov_b32_e32 v30, 0
	v_mov_b32_e32 v31, 0
	v_mov_b32_e32 v32, 0
	v_mov_b32_e32 v33, 0
	s_cbranch_vccnz .LBB0_130
	v_add_co_u32_e32 v28, vcc, 0x60000, v116
	s_nop 1
	v_addc_co_u32_e32 v29, vcc, 0, v117, vcc
	global_load_dwordx4 v[30:33], v[28:29], off nt
.LBB0_130:
	s_and_b64 vcc, exec, s[2:3]
	v_mov_b32_e32 v27, 0
	v_mov_b32_e32 v28, 0
	v_mov_b32_e32 v29, 0
	s_cbranch_vccnz .LBB0_132
	v_add_co_u32_e32 v26, vcc, 0x70000, v116
	s_nop 1
	v_addc_co_u32_e32 v27, vcc, 0, v117, vcc
	global_load_dwordx4 v[26:29], v[26:27], off nt
.LBB0_132:
	v_add_u32_e32 v34, v115, v118
	s_waitcnt vmcnt(0)
	ds_write2_b32 v34, v2, v3 offset1:1
	ds_write2_b32 v34, v4, v5 offset0:2 offset1:3
	v_add_u32_e32 v2, 0x420, v34
	ds_write2_b32 v2, v6, v7 offset1:1
	v_add_u32_e32 v2, 0x428, v34
	ds_write2_b32 v2, v8, v9 offset1:1
	v_add_u32_e32 v2, 0x840, v34
	ds_write2_b32 v2, v14, v15 offset1:1
	v_add_u32_e32 v2, 0x848, v34
	ds_write2_b32 v2, v16, v17 offset1:1
	v_add_u32_e32 v2, 0xc60, v34
	ds_write2_b32 v2, v10, v11 offset1:1
	v_add_u32_e32 v2, 0xc68, v34
	ds_write2_b32 v2, v12, v13 offset1:1
	v_add_u32_e32 v2, 0x1080, v34
	ds_write2_b32 v2, v22, v23 offset1:1
	v_add_u32_e32 v2, 0x1088, v34
	ds_write2_b32 v2, v24, v25 offset1:1
	v_add_u32_e32 v2, 0x14a0, v34
	ds_write2_b32 v2, v18, v19 offset1:1
	v_add_u32_e32 v2, 0x14a8, v34
	ds_write2_b32 v2, v20, v21 offset1:1
	v_add_u32_e32 v2, 0x18c0, v34
	ds_write2_b32 v2, v30, v31 offset1:1
	v_add_u32_e32 v2, 0x18c8, v34
	ds_write2_b32 v2, v32, v33 offset1:1
	v_add_u32_e32 v2, 0x1ce0, v34
	ds_write2_b32 v2, v26, v27 offset1:1
	v_add_u32_e32 v2, 0x1ce8, v34
	ds_write2_b32 v2, v28, v29 offset1:1
	s_mul_i32 s9, s9, 0x1580000
	s_waitcnt lgkmcnt(0)
	s_add_u32 s10, s15, s9
	s_addc_u32 s11, s16, 0
	s_ashr_i32 s9, s8, 31
	ds_read2_b32 v[6:7], v122 offset0:33 offset1:41
	ds_read2_b32 v[8:9], v122 offset1:8
	ds_read2_b32 v[10:11], v122 offset0:66 offset1:74
	ds_read2_b32 v[12:13], v122 offset0:99 offset1:107
	ds_read2_b32 v[14:15], v122 offset0:132 offset1:140
	ds_read2_b32 v[16:17], v122 offset0:165 offset1:173
	ds_read2_b32 v[18:19], v122 offset0:198 offset1:206
	ds_read2_b32 v[20:21], v122 offset0:231 offset1:239
	s_lshl_b64 s[2:3], s[8:9], 1
	s_add_u32 s2, s10, s2
	s_addc_u32 s3, s11, s3
	v_lshlrev_b32_e32 v34, 1, v114
	v_lshl_add_u64 v[22:23], s[2:3], 0, v[34:35]
	s_waitcnt lgkmcnt(6)
	v_cvt_pk_bf16_f32 v2, v8, v6
	v_add_u32_e32 v6, s6, v1
	s_waitcnt lgkmcnt(4)
	v_cvt_pk_bf16_f32 v3, v10, v12
	s_waitcnt lgkmcnt(2)
	v_cvt_pk_bf16_f32 v4, v14, v16
	s_waitcnt lgkmcnt(0)
	v_cvt_pk_bf16_f32 v5, v18, v20
	v_mad_i64_i32 v[24:25], s[2:3], v6, s89, v[22:23]
	global_store_dwordx4 v[24:25], v[2:5], off nt
	v_add_u32_e32 v6, s6, v119
	s_nop 0
	v_cvt_pk_bf16_f32 v2, v9, v7
	v_cvt_pk_bf16_f32 v3, v11, v13
	v_cvt_pk_bf16_f32 v4, v15, v17
	v_cvt_pk_bf16_f32 v5, v19, v21
	ds_read2_b32 v[8:9], v122 offset0:49 offset1:57
	ds_read2_b32 v[10:11], v122 offset0:16 offset1:24
	ds_read2_b32 v[12:13], v122 offset0:82 offset1:90
	ds_read2_b32 v[14:15], v122 offset0:115 offset1:123
	ds_read2_b32 v[16:17], v122 offset0:148 offset1:156
	ds_read2_b32 v[18:19], v122 offset0:181 offset1:189
	ds_read2_b32 v[20:21], v122 offset0:214 offset1:222
	ds_read2_b32 v[24:25], v122 offset0:247 offset1:255
	v_mad_i64_i32 v[6:7], s[2:3], v6, s89, v[22:23]
	global_store_dwordx4 v[6:7], v[2:5], off nt
	v_add_u32_e32 v6, s6, v120
	v_mad_i64_i32 v[6:7], s[2:3], v6, s89, v[22:23]
	s_waitcnt lgkmcnt(6)
	v_cvt_pk_bf16_f32 v2, v10, v8
	s_waitcnt lgkmcnt(4)
	v_cvt_pk_bf16_f32 v3, v12, v14
	s_waitcnt lgkmcnt(2)
	v_cvt_pk_bf16_f32 v4, v16, v18
	s_waitcnt lgkmcnt(0)
	v_cvt_pk_bf16_f32 v5, v20, v24
	global_store_dwordx4 v[6:7], v[2:5], off nt
	v_add_u32_e32 v6, s6, v121
	v_mad_i64_i32 v[6:7], s[2:3], v6, s89, v[22:23]
	v_cvt_pk_bf16_f32 v2, v11, v9
	v_cvt_pk_bf16_f32 v3, v13, v15
	v_cvt_pk_bf16_f32 v4, v17, v19
	v_cvt_pk_bf16_f32 v5, v21, v25
	global_store_dwordx4 v[6:7], v[2:5], off nt
	s_waitcnt lgkmcnt(0)

.LBB0_134:
	s_andn2_b64 vcc, exec, s[2:3]
	s_cbranch_vccnz .LBB0_39
	s_mul_hi_i32 s2, s90, 0x2fa0be83
	s_lshr_b32 s3, s2, 31
	s_ashr_i32 s2, s2, 11
	s_add_i32 s2, s2, s3
	s_mul_i32 s3, s2, 0xffffd500
	s_add_i32 s3, s19, s3
	s_add_i32 s3, s3, 0x13980
	s_mul_hi_i32 s6, s3, 0x2fa0be83
	s_lshr_b32 s8, s6, 31
	s_ashr_i32 s6, s6, 6
	s_add_i32 s6, s6, s8
	s_mul_i32 s8, s6, 0x158
	s_sub_i32 s26, s3, s8
	s_lshl_b32 s34, s26, 5
	v_readlane_b32 s52, v252, 2
	s_bitcmp0_b32 s26, 2
	v_readlane_b32 s66, v252, 16
	v_readlane_b32 s67, v252, 17
	s_cselect_b32 s8, s66, s36
	s_mul_i32 s35, s2, 0x2b00000
	s_cselect_b32 s3, s67, s37
	s_mul_hi_i32 s9, s2, 0x2b00000
	s_add_u32 s2, s8, s35
	s_addc_u32 s3, s3, s9
	s_lshl_b32 s8, s6, 6
	s_lshl_b32 s6, s26, 4
	s_and_b32 s6, s6, 0xffffff80
	s_and_b32 s10, s34, 0x60
	s_or_b32 s6, s6, s10
	s_cmp_gt_i32 s26, -1
	v_add_u32_e32 v4, s8, v1
	v_mov_b64_e32 v[2:3], s[2:3]
	s_movk_i32 s2, 0x5600
	s_cselect_b64 s[10:11], -1, 0
	v_mad_i64_i32 v[2:3], s[2:3], v4, s2, v[2:3]
	s_and_b64 s[2:3], s[10:11], exec
	s_cselect_b32 s6, s6, 0
	v_lshl_add_u64 v[2:3], s[6:7], 2, v[2:3]
	v_lshlrev_b32_e32 v34, 2, v112
	s_cmp_lt_i32 s26, 0
	v_lshl_add_u64 v[116:117], v[2:3], 0, v[34:35]
	v_mov_b32_e32 v6, 0
	v_mov_b32_e32 v2, 0
	v_mov_b32_e32 v3, 0
	v_mov_b32_e32 v4, 0
	v_mov_b32_e32 v5, 0
	v_readlane_b32 s53, v252, 3
	v_readlane_b32 s54, v252, 4
	v_readlane_b32 s55, v252, 5
	v_readlane_b32 s56, v252, 6
	v_readlane_b32 s57, v252, 7
	v_readlane_b32 s58, v252, 8
	v_readlane_b32 s59, v252, 9
	v_readlane_b32 s60, v252, 10
	v_readlane_b32 s61, v252, 11
	v_readlane_b32 s62, v252, 12
	v_readlane_b32 s63, v252, 13
	v_readlane_b32 s64, v252, 14
	v_readlane_b32 s65, v252, 15
	s_cbranch_scc1 .LBB0_137
	global_load_dwordx4 v[2:5], v[116:117], off nt
.LBB0_137:
	v_cndmask_b32_e64 v7, 0, 1, s[10:11]
	v_cmp_ne_u32_e64 s[2:3], 1, v7
	s_andn2_b64 vcc, exec, s[10:11]
	v_mov_b32_e32 v7, 0
	v_mov_b32_e32 v8, 0
	v_mov_b32_e32 v9, 0
	s_cbranch_vccnz .LBB0_139
	v_add_co_u32_e32 v6, vcc, 0x2b000, v116
	s_nop 1
	v_addc_co_u32_e32 v7, vcc, 0, v117, vcc
	global_load_dwordx4 v[6:9], v[6:7], off nt
.LBB0_139:
	v_mov_b32_e32 v10, 0
	s_and_b64 vcc, exec, s[2:3]
	v_mov_b32_e32 v14, 0
	v_mov_b32_e32 v15, 0
	v_mov_b32_e32 v16, 0
	v_mov_b32_e32 v17, 0
	s_cbranch_vccnz .LBB0_141
	v_add_co_u32_e32 v12, vcc, 0x56000, v116
	s_nop 1
	v_addc_co_u32_e32 v13, vcc, 0, v117, vcc
	global_load_dwordx4 v[14:17], v[12:13], off nt
.LBB0_141:
	s_and_b64 vcc, exec, s[2:3]
	v_mov_b32_e32 v11, 0
	v_mov_b32_e32 v12, 0
	v_mov_b32_e32 v13, 0
	s_cbranch_vccnz .LBB0_143
	v_add_co_u32_e32 v10, vcc, 0x81000, v116
	s_nop 1
	v_addc_co_u32_e32 v11, vcc, 0, v117, vcc
	global_load_dwordx4 v[10:13], v[10:11], off nt
.LBB0_143:
	v_mov_b32_e32 v18, 0
	s_and_b64 vcc, exec, s[2:3]
	v_mov_b32_e32 v22, 0
	v_mov_b32_e32 v23, 0
	v_mov_b32_e32 v24, 0
	v_mov_b32_e32 v25, 0
	s_cbranch_vccnz .LBB0_145
	v_add_co_u32_e32 v20, vcc, 0xac000, v116
	s_nop 1
	v_addc_co_u32_e32 v21, vcc, 0, v117, vcc
	global_load_dwordx4 v[22:25], v[20:21], off nt
.LBB0_145:
	s_and_b64 vcc, exec, s[2:3]
	v_mov_b32_e32 v19, 0
	v_mov_b32_e32 v20, 0
	v_mov_b32_e32 v21, 0
	s_cbranch_vccnz .LBB0_147
	v_add_co_u32_e32 v18, vcc, 0xd7000, v116
	s_nop 1
	v_addc_co_u32_e32 v19, vcc, 0, v117, vcc
	global_load_dwordx4 v[18:21], v[18:19], off nt
.LBB0_147:
	v_mov_b32_e32 v26, 0
	s_and_b64 vcc, exec, s[2:3]
	v_mov_b32_e32 v30, 0
	v_mov_b32_e32 v31, 0
	v_mov_b32_e32 v32, 0
	v_mov_b32_e32 v33, 0
	s_cbranch_vccnz .LBB0_149
	v_add_co_u32_e32 v28, vcc, 0x102000, v116
	s_nop 1
	v_addc_co_u32_e32 v29, vcc, 0, v117, vcc
	global_load_dwordx4 v[30:33], v[28:29], off nt
.LBB0_149:
	s_and_b64 vcc, exec, s[2:3]
	v_mov_b32_e32 v27, 0
	v_mov_b32_e32 v28, 0
	v_mov_b32_e32 v29, 0
	s_cbranch_vccnz .LBB0_38
	v_add_co_u32_e32 v26, vcc, 0x12d000, v116
	s_nop 1
	v_addc_co_u32_e32 v27, vcc, 0, v117, vcc
	global_load_dwordx4 v[26:29], v[26:27], off nt
	s_branch .LBB0_38
